# GEMM K-loops: LDS-DMA loads use SGPR base + 32-bit VGPR offset (no 64-bit VALU adds); staging rebalanced 4+4 loads per load segment; code realigned to baseline layout
# speedup vs baseline: 1.0090x; 1.0090x over previous
.LBB0_140:
	s_add_u32 s2, s22, 0xfff80080
	s_addc_u32 s20, s23, -1
	s_add_i32 s45, 0, 0x10000
	s_cmp_eq_u32 s44, 28
	s_cselect_b32 s25, s15, s20
	s_cselect_b32 s24, s40, s2
	v_add_u32_e32 v144, s45, v148
	s_cselect_b32 s21, s13, s43
	s_cselect_b32 s20, s41, s42
	s_add_u32 s100, s22, 0xfff80000
	s_addc_u32 s101, s23, -1
	s_add_i32 s2, 0, 0x14000
	ds_read_b128 v[140:143], v144
	ds_read_b128 v[152:155], v144 offset:1024
	ds_read_b128 v[156:159], v144 offset:2048
	ds_read_b128 v[160:163], v144 offset:3072
	v_add_u32_e32 v144, s2, v148
	ds_read_b128 v[164:167], v144
	ds_read_b128 v[168:171], v144 offset:1024
	ds_read_b128 v[172:175], v144 offset:2048
	ds_read_b128 v[176:179], v144 offset:3072
	s_add_i32 m0, s29, 0xc000
	ds_read_b128 v[180:183], v151
	ds_read_b128 v[184:187], v151 offset:1024
	ds_read_b128 v[188:191], v151 offset:2048
	ds_read_b128 v[192:195], v151 offset:3072
	ds_read_b128 v[206:209], v151 offset:4096
	ds_read_b128 v[210:213], v151 offset:5120
	ds_read_b128 v[214:217], v151 offset:6144
	ds_read_b128 v[218:221], v151 offset:7168
	s_mov_b32 m0, s35
	s_nop 0
	global_load_lds_dwordx4 v136, s[100:101]
	s_mov_b32 m0, s36
	s_nop 0
	global_load_lds_dwordx4 v138, s[100:101]
	s_add_i32 m0, s29, 0xc000
	s_nop 0
	global_load_lds_dwordx4 v136, s[22:23]
	s_add_i32 m0, s29, 0xe000
	s_nop 0
	global_load_lds_dwordx4 v138, s[22:23]
	s_waitcnt vmcnt(8)
	s_waitcnt lgkmcnt(0)
	s_barrier
	s_setprio 1
	s_waitcnt lgkmcnt(0)
	v_mfma_f32_16x16x32_bf16 v[126:129], v[140:143], v[180:183], v[126:129]
	v_mfma_f32_16x16x32_bf16 v[122:125], v[156:159], v[180:183], v[122:125]
	v_mfma_f32_16x16x32_bf16 v[110:113], v[140:143], v[188:191], v[110:113]
	v_mfma_f32_16x16x32_bf16 v[106:109], v[156:159], v[188:191], v[106:109]
	v_mfma_f32_16x16x32_bf16 v[94:97], v[140:143], v[206:209], v[94:97]
	v_mfma_f32_16x16x32_bf16 v[90:93], v[156:159], v[206:209], v[90:93]
	v_mfma_f32_16x16x32_bf16 v[78:81], v[140:143], v[214:217], v[78:81]
	v_mfma_f32_16x16x32_bf16 v[74:77], v[156:159], v[214:217], v[74:77]
	v_mfma_f32_16x16x32_bf16 v[126:129], v[152:155], v[184:187], v[126:129]
	v_mfma_f32_16x16x32_bf16 v[122:125], v[160:163], v[184:187], v[122:125]
	v_mfma_f32_16x16x32_bf16 v[110:113], v[152:155], v[192:195], v[110:113]
	v_mfma_f32_16x16x32_bf16 v[106:109], v[160:163], v[192:195], v[106:109]
	v_mfma_f32_16x16x32_bf16 v[94:97], v[152:155], v[210:213], v[94:97]
	v_mfma_f32_16x16x32_bf16 v[90:93], v[160:163], v[210:213], v[90:93]
	v_mfma_f32_16x16x32_bf16 v[78:81], v[152:155], v[218:221], v[78:81]
	v_mfma_f32_16x16x32_bf16 v[74:77], v[160:163], v[218:221], v[74:77]
	s_setprio 0
	s_setprio 1
	v_mfma_f32_16x16x32_bf16 v[118:121], v[164:167], v[180:183], v[118:121]
	v_mfma_f32_16x16x32_bf16 v[114:117], v[172:175], v[180:183], v[114:117]
	v_mfma_f32_16x16x32_bf16 v[102:105], v[164:167], v[188:191], v[102:105]
	v_mfma_f32_16x16x32_bf16 v[98:101], v[172:175], v[188:191], v[98:101]
	v_mfma_f32_16x16x32_bf16 v[86:89], v[164:167], v[206:209], v[86:89]
	v_mfma_f32_16x16x32_bf16 v[82:85], v[172:175], v[206:209], v[82:85]
	v_mfma_f32_16x16x32_bf16 v[70:73], v[164:167], v[214:217], v[70:73]
	v_mfma_f32_16x16x32_bf16 v[66:69], v[172:175], v[214:217], v[66:69]
	v_mfma_f32_16x16x32_bf16 v[118:121], v[168:171], v[184:187], v[118:121]
	v_mfma_f32_16x16x32_bf16 v[114:117], v[176:179], v[184:187], v[114:117]
	v_mfma_f32_16x16x32_bf16 v[102:105], v[168:171], v[192:195], v[102:105]
	v_mfma_f32_16x16x32_bf16 v[98:101], v[176:179], v[192:195], v[98:101]
	v_mfma_f32_16x16x32_bf16 v[86:89], v[168:171], v[210:213], v[86:89]
	v_mfma_f32_16x16x32_bf16 v[82:85], v[176:179], v[210:213], v[82:85]
	v_mfma_f32_16x16x32_bf16 v[70:73], v[168:171], v[218:221], v[70:73]
	v_mfma_f32_16x16x32_bf16 v[66:69], v[176:179], v[218:221], v[66:69]
	s_setprio 0
	s_barrier
	s_add_u32 s46, s20, 0x80000
	s_addc_u32 s47, s21, 0
	s_add_i32 s45, s45, s28
	s_mov_b32 m0, s45
	ds_read_b128 v[180:183], v151 offset:16384
	ds_read_b128 v[184:187], v151 offset:17408
	ds_read_b128 v[188:191], v151 offset:18432
	ds_read_b128 v[192:195], v151 offset:19456
	ds_read_b128 v[206:209], v151 offset:20480
	ds_read_b128 v[210:213], v151 offset:21504
	ds_read_b128 v[214:217], v151 offset:22528
	ds_read_b128 v[218:221], v151 offset:23552
	global_load_lds_dwordx4 v0, s[20:21]
	s_add_i32 m0, s45, 0x2000
	s_add_i32 s2, s2, s28
	global_load_lds_dwordx4 v130, s[20:21]
	s_mov_b32 m0, s2
	s_nop 0
	global_load_lds_dwordx4 v0, s[46:47]
	s_add_i32 m0, s2, 0x2000
	s_nop 0
	global_load_lds_dwordx4 v130, s[46:47]
	s_waitcnt vmcnt(6)
	s_waitcnt lgkmcnt(0)
	s_barrier
	s_setprio 1
	s_waitcnt lgkmcnt(0)
	v_mfma_f32_16x16x32_bf16 v[62:65], v[140:143], v[180:183], v[62:65]
	v_mfma_f32_16x16x32_bf16 v[58:61], v[156:159], v[180:183], v[58:61]
	v_mfma_f32_16x16x32_bf16 v[46:49], v[140:143], v[188:191], v[46:49]
	v_mfma_f32_16x16x32_bf16 v[42:45], v[156:159], v[188:191], v[42:45]
	v_mfma_f32_16x16x32_bf16 v[30:33], v[140:143], v[206:209], v[30:33]
	v_mfma_f32_16x16x32_bf16 v[26:29], v[156:159], v[206:209], v[26:29]
	v_mfma_f32_16x16x32_bf16 v[14:17], v[140:143], v[214:217], v[14:17]
	v_mfma_f32_16x16x32_bf16 v[10:13], v[156:159], v[214:217], v[10:13]
	v_mfma_f32_16x16x32_bf16 v[62:65], v[152:155], v[184:187], v[62:65]
	v_mfma_f32_16x16x32_bf16 v[58:61], v[160:163], v[184:187], v[58:61]
	v_mfma_f32_16x16x32_bf16 v[46:49], v[152:155], v[192:195], v[46:49]
	v_mfma_f32_16x16x32_bf16 v[42:45], v[160:163], v[192:195], v[42:45]
	v_mfma_f32_16x16x32_bf16 v[30:33], v[152:155], v[210:213], v[30:33]
	v_mfma_f32_16x16x32_bf16 v[26:29], v[160:163], v[210:213], v[26:29]
	v_mfma_f32_16x16x32_bf16 v[14:17], v[152:155], v[218:221], v[14:17]
	v_mfma_f32_16x16x32_bf16 v[10:13], v[160:163], v[218:221], v[10:13]
	s_setprio 0
	s_setprio 1
	v_mfma_f32_16x16x32_bf16 v[54:57], v[164:167], v[180:183], v[54:57]
	v_mfma_f32_16x16x32_bf16 v[50:53], v[172:175], v[180:183], v[50:53]
	v_mfma_f32_16x16x32_bf16 v[38:41], v[164:167], v[188:191], v[38:41]
	v_mfma_f32_16x16x32_bf16 v[34:37], v[172:175], v[188:191], v[34:37]
	v_mfma_f32_16x16x32_bf16 v[22:25], v[164:167], v[206:209], v[22:25]
	v_mfma_f32_16x16x32_bf16 v[18:21], v[172:175], v[206:209], v[18:21]
	v_mfma_f32_16x16x32_bf16 v[6:9], v[164:167], v[214:217], v[6:9]
	v_mfma_f32_16x16x32_bf16 v[2:5], v[172:175], v[214:217], v[2:5]
	v_mfma_f32_16x16x32_bf16 v[54:57], v[168:171], v[184:187], v[54:57]
	v_mfma_f32_16x16x32_bf16 v[50:53], v[176:179], v[184:187], v[50:53]
	v_mfma_f32_16x16x32_bf16 v[38:41], v[168:171], v[192:195], v[38:41]
	v_mfma_f32_16x16x32_bf16 v[34:37], v[176:179], v[192:195], v[34:37]
	v_mfma_f32_16x16x32_bf16 v[22:25], v[168:171], v[210:213], v[22:25]
	v_mfma_f32_16x16x32_bf16 v[18:21], v[176:179], v[210:213], v[18:21]
	v_mfma_f32_16x16x32_bf16 v[6:9], v[168:171], v[218:221], v[6:9]
	v_mfma_f32_16x16x32_bf16 v[2:5], v[176:179], v[218:221], v[2:5]
	s_setprio 0
	s_barrier
	s_add_u32 s24, s24, 0x80000
	s_addc_u32 s25, s25, 0
	s_add_u32 s100, s24, 0xfff80000
	s_addc_u32 s101, s25, -1
	s_add_i32 s2, 0, 0x18000
	s_add_i32 s45, 0, 0x1c000
	v_add_u32_e32 v160, s2, v148
	v_add_u32_e32 v176, s45, v148
	ds_read_b128 v[140:143], v160
	ds_read_b128 v[152:155], v160 offset:1024
	ds_read_b128 v[156:159], v160 offset:2048
	ds_read_b128 v[160:163], v160 offset:3072
	ds_read_b128 v[164:167], v176
	ds_read_b128 v[168:171], v176 offset:1024
	ds_read_b128 v[172:175], v176 offset:2048
	ds_read_b128 v[176:179], v176 offset:3072
	s_mov_b32 m0, s31
	ds_read_b128 v[180:183], v151 offset:32768
	ds_read_b128 v[184:187], v151 offset:33792
	ds_read_b128 v[188:191], v151 offset:34816
	ds_read_b128 v[192:195], v151 offset:35840
	ds_read_b128 v[206:209], v151 offset:36864
	ds_read_b128 v[210:213], v151 offset:37888
	ds_read_b128 v[214:217], v151 offset:38912
	ds_read_b128 v[218:221], v151 offset:39936
	s_mov_b32 m0, s29
	s_nop 0
	global_load_lds_dwordx4 v134, s[100:101]
	s_mov_b32 m0, s30
	s_nop 0
	global_load_lds_dwordx4 v132, s[100:101]
	s_mov_b32 m0, s31
	s_nop 0
	global_load_lds_dwordx4 v134, s[24:25]
	s_mov_b32 m0, s33
	s_nop 0
	global_load_lds_dwordx4 v132, s[24:25]
	s_waitcnt vmcnt(8)
	s_waitcnt lgkmcnt(0)
	s_barrier
	s_setprio 1
	s_waitcnt lgkmcnt(0)
	v_mfma_f32_16x16x32_bf16 v[126:129], v[140:143], v[180:183], v[126:129]
	v_mfma_f32_16x16x32_bf16 v[122:125], v[156:159], v[180:183], v[122:125]
	v_mfma_f32_16x16x32_bf16 v[110:113], v[140:143], v[188:191], v[110:113]
	v_mfma_f32_16x16x32_bf16 v[106:109], v[156:159], v[188:191], v[106:109]
	v_mfma_f32_16x16x32_bf16 v[94:97], v[140:143], v[206:209], v[94:97]
	v_mfma_f32_16x16x32_bf16 v[90:93], v[156:159], v[206:209], v[90:93]
	v_mfma_f32_16x16x32_bf16 v[78:81], v[140:143], v[214:217], v[78:81]
	v_mfma_f32_16x16x32_bf16 v[74:77], v[156:159], v[214:217], v[74:77]
	v_mfma_f32_16x16x32_bf16 v[126:129], v[152:155], v[184:187], v[126:129]
	v_mfma_f32_16x16x32_bf16 v[122:125], v[160:163], v[184:187], v[122:125]
	v_mfma_f32_16x16x32_bf16 v[110:113], v[152:155], v[192:195], v[110:113]
	v_mfma_f32_16x16x32_bf16 v[106:109], v[160:163], v[192:195], v[106:109]
	v_mfma_f32_16x16x32_bf16 v[94:97], v[152:155], v[210:213], v[94:97]
	v_mfma_f32_16x16x32_bf16 v[90:93], v[160:163], v[210:213], v[90:93]
	v_mfma_f32_16x16x32_bf16 v[78:81], v[152:155], v[218:221], v[78:81]
	v_mfma_f32_16x16x32_bf16 v[74:77], v[160:163], v[218:221], v[74:77]
	s_setprio 0
	s_setprio 1
	v_mfma_f32_16x16x32_bf16 v[118:121], v[164:167], v[180:183], v[118:121]
	v_mfma_f32_16x16x32_bf16 v[114:117], v[172:175], v[180:183], v[114:117]
	v_mfma_f32_16x16x32_bf16 v[102:105], v[164:167], v[188:191], v[102:105]
	v_mfma_f32_16x16x32_bf16 v[98:101], v[172:175], v[188:191], v[98:101]
	v_mfma_f32_16x16x32_bf16 v[86:89], v[164:167], v[206:209], v[86:89]
	v_mfma_f32_16x16x32_bf16 v[82:85], v[172:175], v[206:209], v[82:85]
	v_mfma_f32_16x16x32_bf16 v[70:73], v[164:167], v[214:217], v[70:73]
	v_mfma_f32_16x16x32_bf16 v[66:69], v[172:175], v[214:217], v[66:69]
	v_mfma_f32_16x16x32_bf16 v[118:121], v[168:171], v[184:187], v[118:121]
	v_mfma_f32_16x16x32_bf16 v[114:117], v[176:179], v[184:187], v[114:117]
	v_mfma_f32_16x16x32_bf16 v[102:105], v[168:171], v[192:195], v[102:105]
	v_mfma_f32_16x16x32_bf16 v[98:101], v[176:179], v[192:195], v[98:101]
	v_mfma_f32_16x16x32_bf16 v[86:89], v[168:171], v[210:213], v[86:89]
	v_mfma_f32_16x16x32_bf16 v[82:85], v[176:179], v[210:213], v[82:85]
	v_mfma_f32_16x16x32_bf16 v[70:73], v[168:171], v[218:221], v[70:73]
	v_mfma_f32_16x16x32_bf16 v[66:69], v[176:179], v[218:221], v[66:69]
	s_setprio 0
	s_barrier
	s_add_u32 s20, s20, 0x80080
	s_addc_u32 s21, s21, 0
	s_add_u32 s46, s46, 0xfff80080
	s_addc_u32 s47, s47, -1
	s_add_i32 s2, s2, s28
	s_mov_b32 m0, s2
	ds_read_b128 v[180:183], v151 offset:49152
	ds_read_b128 v[184:187], v151 offset:50176
	ds_read_b128 v[188:191], v151 offset:51200
	ds_read_b128 v[192:195], v151 offset:52224
	ds_read_b128 v[206:209], v151 offset:53248
	ds_read_b128 v[210:213], v151 offset:54272
	ds_read_b128 v[214:217], v151 offset:55296
	ds_read_b128 v[218:221], v151 offset:56320
	global_load_lds_dwordx4 v0, s[46:47]
	s_add_i32 m0, s2, 0x2000
	s_add_i32 s2, s45, s28
	global_load_lds_dwordx4 v130, s[46:47]
	s_mov_b32 m0, s2
	s_nop 0
	global_load_lds_dwordx4 v0, s[20:21]
	s_add_i32 m0, s2, 0x2000
	s_nop 0
	global_load_lds_dwordx4 v130, s[20:21]
	s_waitcnt vmcnt(6)
	s_waitcnt lgkmcnt(0)
	s_barrier
	s_setprio 1
	s_waitcnt lgkmcnt(0)
	v_mfma_f32_16x16x32_bf16 v[62:65], v[140:143], v[180:183], v[62:65]
	v_mfma_f32_16x16x32_bf16 v[58:61], v[156:159], v[180:183], v[58:61]
	v_mfma_f32_16x16x32_bf16 v[46:49], v[140:143], v[188:191], v[46:49]
	v_mfma_f32_16x16x32_bf16 v[42:45], v[156:159], v[188:191], v[42:45]
	v_mfma_f32_16x16x32_bf16 v[30:33], v[140:143], v[206:209], v[30:33]
	v_mfma_f32_16x16x32_bf16 v[26:29], v[156:159], v[206:209], v[26:29]
	v_mfma_f32_16x16x32_bf16 v[14:17], v[140:143], v[214:217], v[14:17]
	v_mfma_f32_16x16x32_bf16 v[10:13], v[156:159], v[214:217], v[10:13]
	v_mfma_f32_16x16x32_bf16 v[62:65], v[152:155], v[184:187], v[62:65]
	v_mfma_f32_16x16x32_bf16 v[58:61], v[160:163], v[184:187], v[58:61]
	v_mfma_f32_16x16x32_bf16 v[46:49], v[152:155], v[192:195], v[46:49]
	v_mfma_f32_16x16x32_bf16 v[42:45], v[160:163], v[192:195], v[42:45]
	v_mfma_f32_16x16x32_bf16 v[30:33], v[152:155], v[210:213], v[30:33]
	v_mfma_f32_16x16x32_bf16 v[26:29], v[160:163], v[210:213], v[26:29]
	v_mfma_f32_16x16x32_bf16 v[14:17], v[152:155], v[218:221], v[14:17]
	v_mfma_f32_16x16x32_bf16 v[10:13], v[160:163], v[218:221], v[10:13]
	s_setprio 0
	s_setprio 1
	v_mfma_f32_16x16x32_bf16 v[54:57], v[164:167], v[180:183], v[54:57]
	v_mfma_f32_16x16x32_bf16 v[50:53], v[172:175], v[180:183], v[50:53]
	v_mfma_f32_16x16x32_bf16 v[38:41], v[164:167], v[188:191], v[38:41]
	v_mfma_f32_16x16x32_bf16 v[34:37], v[172:175], v[188:191], v[34:37]
	v_mfma_f32_16x16x32_bf16 v[22:25], v[164:167], v[206:209], v[22:25]
	v_mfma_f32_16x16x32_bf16 v[18:21], v[172:175], v[206:209], v[18:21]
	v_mfma_f32_16x16x32_bf16 v[6:9], v[164:167], v[214:217], v[6:9]
	v_mfma_f32_16x16x32_bf16 v[2:5], v[172:175], v[214:217], v[2:5]
	v_mfma_f32_16x16x32_bf16 v[54:57], v[168:171], v[184:187], v[54:57]
	v_mfma_f32_16x16x32_bf16 v[50:53], v[176:179], v[184:187], v[50:53]
	v_mfma_f32_16x16x32_bf16 v[38:41], v[168:171], v[192:195], v[38:41]
	v_mfma_f32_16x16x32_bf16 v[34:37], v[176:179], v[192:195], v[34:37]
	v_mfma_f32_16x16x32_bf16 v[22:25], v[168:171], v[210:213], v[22:25]
	v_mfma_f32_16x16x32_bf16 v[18:21], v[176:179], v[210:213], v[18:21]
	v_mfma_f32_16x16x32_bf16 v[6:9], v[168:171], v[218:221], v[6:9]
	v_mfma_f32_16x16x32_bf16 v[2:5], v[176:179], v[218:221], v[2:5]
	s_setprio 0
	s_barrier
	s_add_i32 s44, s44, 2
	s_add_u32 s22, s22, 0x100
	s_addc_u32 s23, s23, 0
	s_add_u32 s42, s42, 0x100
	s_addc_u32 s43, s43, 0
	s_cmp_gt_u32 s44, 29
	s_cbranch_scc0 .LBB0_140
	s_nop 0
	s_and_b64 vcc, exec, s[10:11]
	s_cbranch_vccz .LBB0_143
	s_barrier

.LBB0_168:
	s_add_u32 s2, s26, 0xfff80080
	s_addc_u32 s24, s27, -1
	s_add_i32 s50, 0, 0x10000
	s_cmp_eq_u32 s49, 28
	s_cselect_b32 s29, s19, s24
	s_cselect_b32 s28, s44, s2
	v_add_u32_e32 v144, s50, v152
	s_cselect_b32 s25, s17, s47
	s_cselect_b32 s24, s45, s46
	s_add_u32 s100, s26, 0xfff80000
	s_addc_u32 s101, s27, -1
	s_add_i32 s2, 0, 0x14000
	ds_read_b128 v[140:143], v144
	ds_read_b128 v[148:151], v144 offset:1024
	ds_read_b128 v[156:159], v144 offset:2048
	ds_read_b128 v[160:163], v144 offset:3072
	v_add_u32_e32 v144, s2, v152
	ds_read_b128 v[164:167], v144
	ds_read_b128 v[168:171], v144 offset:1024
	ds_read_b128 v[172:175], v144 offset:2048
	ds_read_b128 v[176:179], v144 offset:3072
	s_add_i32 m0, s33, 0xc000
	ds_read_b128 v[180:183], v155
	ds_read_b128 v[184:187], v155 offset:1024
	ds_read_b128 v[188:191], v155 offset:2048
	ds_read_b128 v[192:195], v155 offset:3072
	ds_read_b128 v[206:209], v155 offset:4096
	ds_read_b128 v[210:213], v155 offset:5120
	ds_read_b128 v[214:217], v155 offset:6144
	ds_read_b128 v[218:221], v155 offset:7168
	s_mov_b32 m0, s39
	s_nop 0
	global_load_lds_dwordx4 v136, s[100:101]
	s_mov_b32 m0, s40
	s_nop 0
	global_load_lds_dwordx4 v138, s[100:101]
	s_add_i32 m0, s33, 0xc000
	s_nop 0
	global_load_lds_dwordx4 v136, s[26:27]
	s_add_i32 m0, s33, 0xe000
	s_nop 0
	global_load_lds_dwordx4 v138, s[26:27]
	s_waitcnt vmcnt(8)
	s_waitcnt lgkmcnt(0)
	s_barrier
	s_setprio 1
	s_waitcnt lgkmcnt(0)
	v_mfma_f32_16x16x32_bf16 v[122:125], v[140:143], v[180:183], v[122:125]
	v_mfma_f32_16x16x32_bf16 v[114:117], v[156:159], v[180:183], v[114:117]
	v_mfma_f32_16x16x32_bf16 v[106:109], v[140:143], v[188:191], v[106:109]
	v_mfma_f32_16x16x32_bf16 v[98:101], v[156:159], v[188:191], v[98:101]
	v_mfma_f32_16x16x32_bf16 v[90:93], v[140:143], v[206:209], v[90:93]
	v_mfma_f32_16x16x32_bf16 v[82:85], v[156:159], v[206:209], v[82:85]
	v_mfma_f32_16x16x32_bf16 v[74:77], v[140:143], v[214:217], v[74:77]
	v_mfma_f32_16x16x32_bf16 v[66:69], v[156:159], v[214:217], v[66:69]
	v_mfma_f32_16x16x32_bf16 v[122:125], v[148:151], v[184:187], v[122:125]
	v_mfma_f32_16x16x32_bf16 v[114:117], v[160:163], v[184:187], v[114:117]
	v_mfma_f32_16x16x32_bf16 v[106:109], v[148:151], v[192:195], v[106:109]
	v_mfma_f32_16x16x32_bf16 v[98:101], v[160:163], v[192:195], v[98:101]
	v_mfma_f32_16x16x32_bf16 v[90:93], v[148:151], v[210:213], v[90:93]
	v_mfma_f32_16x16x32_bf16 v[82:85], v[160:163], v[210:213], v[82:85]
	v_mfma_f32_16x16x32_bf16 v[74:77], v[148:151], v[218:221], v[74:77]
	v_mfma_f32_16x16x32_bf16 v[66:69], v[160:163], v[218:221], v[66:69]
	s_setprio 0
	s_setprio 1
	v_mfma_f32_16x16x32_bf16 v[126:129], v[164:167], v[180:183], v[126:129]
	v_mfma_f32_16x16x32_bf16 v[118:121], v[172:175], v[180:183], v[118:121]
	v_mfma_f32_16x16x32_bf16 v[110:113], v[164:167], v[188:191], v[110:113]
	v_mfma_f32_16x16x32_bf16 v[102:105], v[172:175], v[188:191], v[102:105]
	v_mfma_f32_16x16x32_bf16 v[94:97], v[164:167], v[206:209], v[94:97]
	v_mfma_f32_16x16x32_bf16 v[86:89], v[172:175], v[206:209], v[86:89]
	v_mfma_f32_16x16x32_bf16 v[78:81], v[164:167], v[214:217], v[78:81]
	v_mfma_f32_16x16x32_bf16 v[70:73], v[172:175], v[214:217], v[70:73]
	v_mfma_f32_16x16x32_bf16 v[126:129], v[168:171], v[184:187], v[126:129]
	v_mfma_f32_16x16x32_bf16 v[118:121], v[176:179], v[184:187], v[118:121]
	v_mfma_f32_16x16x32_bf16 v[110:113], v[168:171], v[192:195], v[110:113]
	v_mfma_f32_16x16x32_bf16 v[102:105], v[176:179], v[192:195], v[102:105]
	v_mfma_f32_16x16x32_bf16 v[94:97], v[168:171], v[210:213], v[94:97]
	v_mfma_f32_16x16x32_bf16 v[86:89], v[176:179], v[210:213], v[86:89]
	v_mfma_f32_16x16x32_bf16 v[78:81], v[168:171], v[218:221], v[78:81]
	v_mfma_f32_16x16x32_bf16 v[70:73], v[176:179], v[218:221], v[70:73]
	s_setprio 0
	s_barrier
	s_add_u32 s52, s24, 0x80000
	s_addc_u32 s53, s25, 0
	s_add_i32 s50, s50, s35
	s_mov_b32 m0, s50
	ds_read_b128 v[180:183], v155 offset:16384
	ds_read_b128 v[184:187], v155 offset:17408
	ds_read_b128 v[188:191], v155 offset:18432
	ds_read_b128 v[192:195], v155 offset:19456
	ds_read_b128 v[206:209], v155 offset:20480
	ds_read_b128 v[210:213], v155 offset:21504
	ds_read_b128 v[214:217], v155 offset:22528
	ds_read_b128 v[218:221], v155 offset:23552
	global_load_lds_dwordx4 v0, s[24:25]
	s_add_i32 m0, s50, 0x2000
	s_add_i32 s2, s2, s35
	global_load_lds_dwordx4 v130, s[24:25]
	s_mov_b32 m0, s2
	s_nop 0
	global_load_lds_dwordx4 v0, s[52:53]
	s_add_i32 m0, s2, 0x2000
	s_nop 0
	global_load_lds_dwordx4 v130, s[52:53]
	s_waitcnt vmcnt(6)
	s_waitcnt lgkmcnt(0)
	s_barrier
	s_setprio 1
	s_waitcnt lgkmcnt(0)
	v_mfma_f32_16x16x32_bf16 v[58:61], v[140:143], v[180:183], v[58:61]
	v_mfma_f32_16x16x32_bf16 v[50:53], v[156:159], v[180:183], v[50:53]
	v_mfma_f32_16x16x32_bf16 v[42:45], v[140:143], v[188:191], v[42:45]
	v_mfma_f32_16x16x32_bf16 v[34:37], v[156:159], v[188:191], v[34:37]
	v_mfma_f32_16x16x32_bf16 v[26:29], v[140:143], v[206:209], v[26:29]
	v_mfma_f32_16x16x32_bf16 v[18:21], v[156:159], v[206:209], v[18:21]
	v_mfma_f32_16x16x32_bf16 v[10:13], v[140:143], v[214:217], v[10:13]
	v_mfma_f32_16x16x32_bf16 v[6:9], v[156:159], v[214:217], v[6:9]
	v_mfma_f32_16x16x32_bf16 v[58:61], v[148:151], v[184:187], v[58:61]
	v_mfma_f32_16x16x32_bf16 v[50:53], v[160:163], v[184:187], v[50:53]
	v_mfma_f32_16x16x32_bf16 v[42:45], v[148:151], v[192:195], v[42:45]
	v_mfma_f32_16x16x32_bf16 v[34:37], v[160:163], v[192:195], v[34:37]
	v_mfma_f32_16x16x32_bf16 v[26:29], v[148:151], v[210:213], v[26:29]
	v_mfma_f32_16x16x32_bf16 v[18:21], v[160:163], v[210:213], v[18:21]
	v_mfma_f32_16x16x32_bf16 v[10:13], v[148:151], v[218:221], v[10:13]
	v_mfma_f32_16x16x32_bf16 v[6:9], v[160:163], v[218:221], v[6:9]
	s_setprio 0
	s_setprio 1
	v_mfma_f32_16x16x32_bf16 v[62:65], v[164:167], v[180:183], v[62:65]
	v_mfma_f32_16x16x32_bf16 v[54:57], v[172:175], v[180:183], v[54:57]
	v_mfma_f32_16x16x32_bf16 v[46:49], v[164:167], v[188:191], v[46:49]
	v_mfma_f32_16x16x32_bf16 v[38:41], v[172:175], v[188:191], v[38:41]
	v_mfma_f32_16x16x32_bf16 v[30:33], v[164:167], v[206:209], v[30:33]
	v_mfma_f32_16x16x32_bf16 v[22:25], v[172:175], v[206:209], v[22:25]
	v_mfma_f32_16x16x32_bf16 v[14:17], v[164:167], v[214:217], v[14:17]
	v_mfma_f32_16x16x32_bf16 v[2:5], v[172:175], v[214:217], v[2:5]
	v_mfma_f32_16x16x32_bf16 v[62:65], v[168:171], v[184:187], v[62:65]
	v_mfma_f32_16x16x32_bf16 v[54:57], v[176:179], v[184:187], v[54:57]
	v_mfma_f32_16x16x32_bf16 v[46:49], v[168:171], v[192:195], v[46:49]
	v_mfma_f32_16x16x32_bf16 v[38:41], v[176:179], v[192:195], v[38:41]
	v_mfma_f32_16x16x32_bf16 v[30:33], v[168:171], v[210:213], v[30:33]
	v_mfma_f32_16x16x32_bf16 v[22:25], v[176:179], v[210:213], v[22:25]
	v_mfma_f32_16x16x32_bf16 v[14:17], v[168:171], v[218:221], v[14:17]
	v_mfma_f32_16x16x32_bf16 v[2:5], v[176:179], v[218:221], v[2:5]
	s_setprio 0
	s_barrier
	s_add_u32 s28, s28, 0x80000
	s_addc_u32 s29, s29, 0
	s_add_u32 s100, s28, 0xfff80000
	s_addc_u32 s101, s29, -1
	s_add_i32 s2, 0, 0x18000
	s_add_i32 s50, 0, 0x1c000
	v_add_u32_e32 v160, s2, v152
	v_add_u32_e32 v176, s50, v152
	ds_read_b128 v[140:143], v160
	ds_read_b128 v[148:151], v160 offset:1024
	ds_read_b128 v[156:159], v160 offset:2048
	ds_read_b128 v[160:163], v160 offset:3072
	ds_read_b128 v[164:167], v176
	ds_read_b128 v[168:171], v176 offset:1024
	ds_read_b128 v[172:175], v176 offset:2048
	ds_read_b128 v[176:179], v176 offset:3072
	s_mov_b32 m0, s37
	ds_read_b128 v[180:183], v155 offset:32768
	ds_read_b128 v[184:187], v155 offset:33792
	ds_read_b128 v[188:191], v155 offset:34816
	ds_read_b128 v[192:195], v155 offset:35840
	ds_read_b128 v[206:209], v155 offset:36864
	ds_read_b128 v[210:213], v155 offset:37888
	ds_read_b128 v[214:217], v155 offset:38912
	ds_read_b128 v[218:221], v155 offset:39936
	s_mov_b32 m0, s33
	s_nop 0
	global_load_lds_dwordx4 v134, s[100:101]
	s_mov_b32 m0, s36
	s_nop 0
	global_load_lds_dwordx4 v132, s[100:101]
	s_mov_b32 m0, s37
	s_nop 0
	global_load_lds_dwordx4 v134, s[28:29]
	s_mov_b32 m0, s38
	s_nop 0
	global_load_lds_dwordx4 v132, s[28:29]
	s_waitcnt vmcnt(8)
	s_waitcnt lgkmcnt(0)
	s_barrier
	s_setprio 1
	s_waitcnt lgkmcnt(0)
	v_mfma_f32_16x16x32_bf16 v[122:125], v[140:143], v[180:183], v[122:125]
	v_mfma_f32_16x16x32_bf16 v[114:117], v[156:159], v[180:183], v[114:117]
	v_mfma_f32_16x16x32_bf16 v[106:109], v[140:143], v[188:191], v[106:109]
	v_mfma_f32_16x16x32_bf16 v[98:101], v[156:159], v[188:191], v[98:101]
	v_mfma_f32_16x16x32_bf16 v[90:93], v[140:143], v[206:209], v[90:93]
	v_mfma_f32_16x16x32_bf16 v[82:85], v[156:159], v[206:209], v[82:85]
	v_mfma_f32_16x16x32_bf16 v[74:77], v[140:143], v[214:217], v[74:77]
	v_mfma_f32_16x16x32_bf16 v[66:69], v[156:159], v[214:217], v[66:69]
	v_mfma_f32_16x16x32_bf16 v[122:125], v[148:151], v[184:187], v[122:125]
	v_mfma_f32_16x16x32_bf16 v[114:117], v[160:163], v[184:187], v[114:117]
	v_mfma_f32_16x16x32_bf16 v[106:109], v[148:151], v[192:195], v[106:109]
	v_mfma_f32_16x16x32_bf16 v[98:101], v[160:163], v[192:195], v[98:101]
	v_mfma_f32_16x16x32_bf16 v[90:93], v[148:151], v[210:213], v[90:93]
	v_mfma_f32_16x16x32_bf16 v[82:85], v[160:163], v[210:213], v[82:85]
	v_mfma_f32_16x16x32_bf16 v[74:77], v[148:151], v[218:221], v[74:77]
	v_mfma_f32_16x16x32_bf16 v[66:69], v[160:163], v[218:221], v[66:69]
	s_setprio 0
	s_setprio 1
	v_mfma_f32_16x16x32_bf16 v[126:129], v[164:167], v[180:183], v[126:129]
	v_mfma_f32_16x16x32_bf16 v[118:121], v[172:175], v[180:183], v[118:121]
	v_mfma_f32_16x16x32_bf16 v[110:113], v[164:167], v[188:191], v[110:113]
	v_mfma_f32_16x16x32_bf16 v[102:105], v[172:175], v[188:191], v[102:105]
	v_mfma_f32_16x16x32_bf16 v[94:97], v[164:167], v[206:209], v[94:97]
	v_mfma_f32_16x16x32_bf16 v[86:89], v[172:175], v[206:209], v[86:89]
	v_mfma_f32_16x16x32_bf16 v[78:81], v[164:167], v[214:217], v[78:81]
	v_mfma_f32_16x16x32_bf16 v[70:73], v[172:175], v[214:217], v[70:73]
	v_mfma_f32_16x16x32_bf16 v[126:129], v[168:171], v[184:187], v[126:129]
	v_mfma_f32_16x16x32_bf16 v[118:121], v[176:179], v[184:187], v[118:121]
	v_mfma_f32_16x16x32_bf16 v[110:113], v[168:171], v[192:195], v[110:113]
	v_mfma_f32_16x16x32_bf16 v[102:105], v[176:179], v[192:195], v[102:105]
	v_mfma_f32_16x16x32_bf16 v[94:97], v[168:171], v[210:213], v[94:97]
	v_mfma_f32_16x16x32_bf16 v[86:89], v[176:179], v[210:213], v[86:89]
	v_mfma_f32_16x16x32_bf16 v[78:81], v[168:171], v[218:221], v[78:81]
	v_mfma_f32_16x16x32_bf16 v[70:73], v[176:179], v[218:221], v[70:73]
	s_setprio 0
	s_barrier
	s_add_u32 s24, s24, 0x80080
	s_addc_u32 s25, s25, 0
	s_add_u32 s52, s52, 0xfff80080
	s_addc_u32 s53, s53, -1
	s_add_i32 s2, s2, s35
	s_mov_b32 m0, s2
	ds_read_b128 v[180:183], v155 offset:49152
	ds_read_b128 v[184:187], v155 offset:50176
	ds_read_b128 v[188:191], v155 offset:51200
	ds_read_b128 v[192:195], v155 offset:52224
	ds_read_b128 v[206:209], v155 offset:53248
	ds_read_b128 v[210:213], v155 offset:54272
	ds_read_b128 v[214:217], v155 offset:55296
	ds_read_b128 v[218:221], v155 offset:56320
	global_load_lds_dwordx4 v0, s[52:53]
	s_add_i32 m0, s2, 0x2000
	s_add_i32 s2, s50, s35
	global_load_lds_dwordx4 v130, s[52:53]
	s_mov_b32 m0, s2
	s_nop 0
	global_load_lds_dwordx4 v0, s[24:25]
	s_add_i32 m0, s2, 0x2000
	s_nop 0
	global_load_lds_dwordx4 v130, s[24:25]
	s_waitcnt vmcnt(6)
	s_waitcnt lgkmcnt(0)
	s_barrier
	s_setprio 1
	s_waitcnt lgkmcnt(0)
	v_mfma_f32_16x16x32_bf16 v[58:61], v[140:143], v[180:183], v[58:61]
	v_mfma_f32_16x16x32_bf16 v[50:53], v[156:159], v[180:183], v[50:53]
	v_mfma_f32_16x16x32_bf16 v[42:45], v[140:143], v[188:191], v[42:45]
	v_mfma_f32_16x16x32_bf16 v[34:37], v[156:159], v[188:191], v[34:37]
	v_mfma_f32_16x16x32_bf16 v[26:29], v[140:143], v[206:209], v[26:29]
	v_mfma_f32_16x16x32_bf16 v[18:21], v[156:159], v[206:209], v[18:21]
	v_mfma_f32_16x16x32_bf16 v[10:13], v[140:143], v[214:217], v[10:13]
	v_mfma_f32_16x16x32_bf16 v[6:9], v[156:159], v[214:217], v[6:9]
	v_mfma_f32_16x16x32_bf16 v[58:61], v[148:151], v[184:187], v[58:61]
	v_mfma_f32_16x16x32_bf16 v[50:53], v[160:163], v[184:187], v[50:53]
	v_mfma_f32_16x16x32_bf16 v[42:45], v[148:151], v[192:195], v[42:45]
	v_mfma_f32_16x16x32_bf16 v[34:37], v[160:163], v[192:195], v[34:37]
	v_mfma_f32_16x16x32_bf16 v[26:29], v[148:151], v[210:213], v[26:29]
	v_mfma_f32_16x16x32_bf16 v[18:21], v[160:163], v[210:213], v[18:21]
	v_mfma_f32_16x16x32_bf16 v[10:13], v[148:151], v[218:221], v[10:13]
	v_mfma_f32_16x16x32_bf16 v[6:9], v[160:163], v[218:221], v[6:9]
	s_setprio 0
	s_setprio 1
	v_mfma_f32_16x16x32_bf16 v[62:65], v[164:167], v[180:183], v[62:65]
	v_mfma_f32_16x16x32_bf16 v[54:57], v[172:175], v[180:183], v[54:57]
	v_mfma_f32_16x16x32_bf16 v[46:49], v[164:167], v[188:191], v[46:49]
	v_mfma_f32_16x16x32_bf16 v[38:41], v[172:175], v[188:191], v[38:41]
	v_mfma_f32_16x16x32_bf16 v[30:33], v[164:167], v[206:209], v[30:33]
	v_mfma_f32_16x16x32_bf16 v[22:25], v[172:175], v[206:209], v[22:25]
	v_mfma_f32_16x16x32_bf16 v[14:17], v[164:167], v[214:217], v[14:17]
	v_mfma_f32_16x16x32_bf16 v[2:5], v[172:175], v[214:217], v[2:5]
	v_mfma_f32_16x16x32_bf16 v[62:65], v[168:171], v[184:187], v[62:65]
	v_mfma_f32_16x16x32_bf16 v[54:57], v[176:179], v[184:187], v[54:57]
	v_mfma_f32_16x16x32_bf16 v[46:49], v[168:171], v[192:195], v[46:49]
	v_mfma_f32_16x16x32_bf16 v[38:41], v[176:179], v[192:195], v[38:41]
	v_mfma_f32_16x16x32_bf16 v[30:33], v[168:171], v[210:213], v[30:33]
	v_mfma_f32_16x16x32_bf16 v[22:25], v[176:179], v[210:213], v[22:25]
	v_mfma_f32_16x16x32_bf16 v[14:17], v[168:171], v[218:221], v[14:17]
	v_mfma_f32_16x16x32_bf16 v[2:5], v[176:179], v[218:221], v[2:5]
	s_setprio 0
	s_barrier
	s_add_i32 s49, s49, 2
	s_add_u32 s26, s26, 0x100
	s_addc_u32 s27, s27, 0
	s_add_u32 s46, s46, 0x100
	s_addc_u32 s47, s47, 0
	s_cmp_gt_u32 s49, 29
	s_cbranch_scc0 .LBB0_168
	s_nop 0
	s_and_b64 vcc, exec, s[14:15]
	s_cbranch_vccz .LBB0_171
	s_barrier

.LBB0_281:
	s_add_u32 s20, s18, 0x100
	s_addc_u32 s21, s19, 0
	s_add_i32 s2, 0, 0x10000
	s_cmpk_eq_i32 s42, 0x52
	s_cselect_b32 s25, s11, s21
	s_cselect_b32 s24, s10, s20
	s_cselect_b32 s23, s17, s41
	s_cselect_b32 s22, s16, s40
	s_add_u32 s100, s18, 0xffea8000
	s_addc_u32 s101, s19, -1
	s_add_i32 s43, 0, 0x14000
	v_add_u32_e32 v142, s2, v226
	v_add_u32_e32 v160, s43, v226
	ds_read_b128 v[126:129], v142
	ds_read_b128 v[134:137], v142 offset:1024
	ds_read_b128 v[138:141], v142 offset:2048
	ds_read_b128 v[142:145], v142 offset:3072
	ds_read_b128 v[148:151], v160
	ds_read_b128 v[152:155], v160 offset:1024
	ds_read_b128 v[156:159], v160 offset:2048
	ds_read_b128 v[160:163], v160 offset:3072
	s_add_i32 m0, s26, 0xc000
	ds_read_b128 v[164:167], v228
	ds_read_b128 v[168:171], v228 offset:1024
	ds_read_b128 v[172:175], v228 offset:2048
	ds_read_b128 v[176:179], v228 offset:3072
	ds_read_b128 v[180:183], v228 offset:4096
	ds_read_b128 v[184:187], v228 offset:5120
	ds_read_b128 v[208:211], v228 offset:6144
	ds_read_b128 v[212:215], v228 offset:7168
	s_mov_b32 m0, s36
	s_nop 0
	global_load_lds_dwordx4 v194, s[100:101]
	s_mov_b32 m0, s37
	s_nop 0
	global_load_lds_dwordx4 v206, s[100:101]
	s_add_i32 m0, s26, 0xc000
	s_nop 0
	global_load_lds_dwordx4 v194, s[18:19]
	s_add_i32 m0, s26, 0xe000
	s_nop 0
	global_load_lds_dwordx4 v206, s[18:19]
	s_waitcnt vmcnt(8)
	s_waitcnt lgkmcnt(0)
	s_barrier
	s_setprio 1
	s_waitcnt lgkmcnt(0)
	v_mfma_f32_16x16x32_bf16 v[130:133], v[126:129], v[164:167], v[130:133]
	v_mfma_f32_16x16x32_bf16 v[122:125], v[138:141], v[164:167], v[122:125]
	v_mfma_f32_16x16x32_bf16 v[110:113], v[126:129], v[172:175], v[110:113]
	v_mfma_f32_16x16x32_bf16 v[106:109], v[138:141], v[172:175], v[106:109]
	v_mfma_f32_16x16x32_bf16 v[94:97], v[126:129], v[180:183], v[94:97]
	v_mfma_f32_16x16x32_bf16 v[90:93], v[138:141], v[180:183], v[90:93]
	v_mfma_f32_16x16x32_bf16 v[78:81], v[126:129], v[208:211], v[78:81]
	v_mfma_f32_16x16x32_bf16 v[74:77], v[138:141], v[208:211], v[74:77]
	v_mfma_f32_16x16x32_bf16 v[130:133], v[134:137], v[168:171], v[130:133]
	v_mfma_f32_16x16x32_bf16 v[122:125], v[142:145], v[168:171], v[122:125]
	v_mfma_f32_16x16x32_bf16 v[110:113], v[134:137], v[176:179], v[110:113]
	v_mfma_f32_16x16x32_bf16 v[106:109], v[142:145], v[176:179], v[106:109]
	v_mfma_f32_16x16x32_bf16 v[94:97], v[134:137], v[184:187], v[94:97]
	v_mfma_f32_16x16x32_bf16 v[90:93], v[142:145], v[184:187], v[90:93]
	v_mfma_f32_16x16x32_bf16 v[78:81], v[134:137], v[212:215], v[78:81]
	v_mfma_f32_16x16x32_bf16 v[74:77], v[142:145], v[212:215], v[74:77]
	s_setprio 0
	s_setprio 1
	v_mfma_f32_16x16x32_bf16 v[118:121], v[148:151], v[164:167], v[118:121]
	v_mfma_f32_16x16x32_bf16 v[114:117], v[156:159], v[164:167], v[114:117]
	v_mfma_f32_16x16x32_bf16 v[102:105], v[148:151], v[172:175], v[102:105]
	v_mfma_f32_16x16x32_bf16 v[98:101], v[156:159], v[172:175], v[98:101]
	v_mfma_f32_16x16x32_bf16 v[86:89], v[148:151], v[180:183], v[86:89]
	v_mfma_f32_16x16x32_bf16 v[82:85], v[156:159], v[180:183], v[82:85]
	v_mfma_f32_16x16x32_bf16 v[70:73], v[148:151], v[208:211], v[70:73]
	v_mfma_f32_16x16x32_bf16 v[66:69], v[156:159], v[208:211], v[66:69]
	v_mfma_f32_16x16x32_bf16 v[118:121], v[152:155], v[168:171], v[118:121]
	v_mfma_f32_16x16x32_bf16 v[114:117], v[160:163], v[168:171], v[114:117]
	v_mfma_f32_16x16x32_bf16 v[102:105], v[152:155], v[176:179], v[102:105]
	v_mfma_f32_16x16x32_bf16 v[98:101], v[160:163], v[176:179], v[98:101]
	v_mfma_f32_16x16x32_bf16 v[86:89], v[152:155], v[184:187], v[86:89]
	v_mfma_f32_16x16x32_bf16 v[82:85], v[160:163], v[184:187], v[82:85]
	v_mfma_f32_16x16x32_bf16 v[70:73], v[152:155], v[212:215], v[70:73]
	v_mfma_f32_16x16x32_bf16 v[66:69], v[160:163], v[212:215], v[66:69]
	s_setprio 0
	s_barrier
	s_add_u32 s18, s22, 0x158000
	s_addc_u32 s19, s23, 0
	s_add_i32 s2, s2, s1
	s_mov_b32 m0, s2
	ds_read_b128 v[164:167], v228 offset:16384
	ds_read_b128 v[168:171], v228 offset:17408
	ds_read_b128 v[172:175], v228 offset:18432
	ds_read_b128 v[176:179], v228 offset:19456
	ds_read_b128 v[180:183], v228 offset:20480
	ds_read_b128 v[184:187], v228 offset:21504
	ds_read_b128 v[208:211], v228 offset:22528
	ds_read_b128 v[212:215], v228 offset:23552
	global_load_lds_dwordx4 v0, s[22:23]
	s_add_i32 m0, s2, 0x2000
	s_add_i32 s2, s43, s1
	global_load_lds_dwordx4 v188, s[22:23]
	s_mov_b32 m0, s2
	s_nop 0
	global_load_lds_dwordx4 v0, s[18:19]
	s_add_i32 m0, s2, 0x2000
	s_nop 0
	global_load_lds_dwordx4 v188, s[18:19]
	s_waitcnt vmcnt(6)
	s_waitcnt lgkmcnt(0)
	s_barrier
	s_setprio 1
	s_waitcnt lgkmcnt(0)
	v_mfma_f32_16x16x32_bf16 v[62:65], v[126:129], v[164:167], v[62:65]
	v_mfma_f32_16x16x32_bf16 v[58:61], v[138:141], v[164:167], v[58:61]
	v_mfma_f32_16x16x32_bf16 v[46:49], v[126:129], v[172:175], v[46:49]
	v_mfma_f32_16x16x32_bf16 v[42:45], v[138:141], v[172:175], v[42:45]
	v_mfma_f32_16x16x32_bf16 v[30:33], v[126:129], v[180:183], v[30:33]
	v_mfma_f32_16x16x32_bf16 v[26:29], v[138:141], v[180:183], v[26:29]
	v_mfma_f32_16x16x32_bf16 v[14:17], v[126:129], v[208:211], v[14:17]
	v_mfma_f32_16x16x32_bf16 v[10:13], v[138:141], v[208:211], v[10:13]
	v_mfma_f32_16x16x32_bf16 v[62:65], v[134:137], v[168:171], v[62:65]
	v_mfma_f32_16x16x32_bf16 v[58:61], v[142:145], v[168:171], v[58:61]
	v_mfma_f32_16x16x32_bf16 v[46:49], v[134:137], v[176:179], v[46:49]
	v_mfma_f32_16x16x32_bf16 v[42:45], v[142:145], v[176:179], v[42:45]
	v_mfma_f32_16x16x32_bf16 v[30:33], v[134:137], v[184:187], v[30:33]
	v_mfma_f32_16x16x32_bf16 v[26:29], v[142:145], v[184:187], v[26:29]
	v_mfma_f32_16x16x32_bf16 v[14:17], v[134:137], v[212:215], v[14:17]
	v_mfma_f32_16x16x32_bf16 v[10:13], v[142:145], v[212:215], v[10:13]
	s_setprio 0
	s_setprio 1
	v_mfma_f32_16x16x32_bf16 v[54:57], v[148:151], v[164:167], v[54:57]
	v_mfma_f32_16x16x32_bf16 v[50:53], v[156:159], v[164:167], v[50:53]
	v_mfma_f32_16x16x32_bf16 v[38:41], v[148:151], v[172:175], v[38:41]
	v_mfma_f32_16x16x32_bf16 v[34:37], v[156:159], v[172:175], v[34:37]
	v_mfma_f32_16x16x32_bf16 v[22:25], v[148:151], v[180:183], v[22:25]
	v_mfma_f32_16x16x32_bf16 v[18:21], v[156:159], v[180:183], v[18:21]
	v_mfma_f32_16x16x32_bf16 v[6:9], v[148:151], v[208:211], v[6:9]
	v_mfma_f32_16x16x32_bf16 v[2:5], v[156:159], v[208:211], v[2:5]
	v_mfma_f32_16x16x32_bf16 v[54:57], v[152:155], v[168:171], v[54:57]
	v_mfma_f32_16x16x32_bf16 v[50:53], v[160:163], v[168:171], v[50:53]
	v_mfma_f32_16x16x32_bf16 v[38:41], v[152:155], v[176:179], v[38:41]
	v_mfma_f32_16x16x32_bf16 v[34:37], v[160:163], v[176:179], v[34:37]
	v_mfma_f32_16x16x32_bf16 v[22:25], v[152:155], v[184:187], v[22:25]
	v_mfma_f32_16x16x32_bf16 v[18:21], v[160:163], v[184:187], v[18:21]
	v_mfma_f32_16x16x32_bf16 v[6:9], v[152:155], v[212:215], v[6:9]
	v_mfma_f32_16x16x32_bf16 v[2:5], v[160:163], v[212:215], v[2:5]
	s_setprio 0
	s_barrier
	s_add_u32 s18, s24, 0x158000
	s_addc_u32 s19, s25, 0
	s_add_i32 s2, 0, 0x18000
	s_add_i32 s43, 0, 0x1c000
	v_add_u32_e32 v142, s2, v226
	v_add_u32_e32 v160, s43, v226
	ds_read_b128 v[126:129], v142
	ds_read_b128 v[134:137], v142 offset:1024
	ds_read_b128 v[138:141], v142 offset:2048
	ds_read_b128 v[142:145], v142 offset:3072
	ds_read_b128 v[148:151], v160
	ds_read_b128 v[152:155], v160 offset:1024
	ds_read_b128 v[156:159], v160 offset:2048
	ds_read_b128 v[160:163], v160 offset:3072
	s_mov_b32 m0, s30
	ds_read_b128 v[164:167], v228 offset:32768
	ds_read_b128 v[168:171], v228 offset:33792
	ds_read_b128 v[172:175], v228 offset:34816
	ds_read_b128 v[176:179], v228 offset:35840
	ds_read_b128 v[180:183], v228 offset:36864
	ds_read_b128 v[184:187], v228 offset:37888
	ds_read_b128 v[208:211], v228 offset:38912
	ds_read_b128 v[212:215], v228 offset:39936
	s_mov_b32 m0, s26
	s_nop 0
	global_load_lds_dwordx4 v192, s[24:25]
	s_mov_b32 m0, s27
	s_nop 0
	global_load_lds_dwordx4 v190, s[24:25]
	s_mov_b32 m0, s30
	s_nop 0
	global_load_lds_dwordx4 v192, s[18:19]
	s_mov_b32 m0, s31
	s_nop 0
	global_load_lds_dwordx4 v190, s[18:19]
	s_waitcnt vmcnt(8)
	s_waitcnt lgkmcnt(0)
	s_barrier
	s_setprio 1
	s_waitcnt lgkmcnt(0)
	v_mfma_f32_16x16x32_bf16 v[130:133], v[126:129], v[164:167], v[130:133]
	v_mfma_f32_16x16x32_bf16 v[122:125], v[138:141], v[164:167], v[122:125]
	v_mfma_f32_16x16x32_bf16 v[110:113], v[126:129], v[172:175], v[110:113]
	v_mfma_f32_16x16x32_bf16 v[106:109], v[138:141], v[172:175], v[106:109]
	v_mfma_f32_16x16x32_bf16 v[94:97], v[126:129], v[180:183], v[94:97]
	v_mfma_f32_16x16x32_bf16 v[90:93], v[138:141], v[180:183], v[90:93]
	v_mfma_f32_16x16x32_bf16 v[78:81], v[126:129], v[208:211], v[78:81]
	v_mfma_f32_16x16x32_bf16 v[74:77], v[138:141], v[208:211], v[74:77]
	v_mfma_f32_16x16x32_bf16 v[130:133], v[134:137], v[168:171], v[130:133]
	v_mfma_f32_16x16x32_bf16 v[122:125], v[142:145], v[168:171], v[122:125]
	v_mfma_f32_16x16x32_bf16 v[110:113], v[134:137], v[176:179], v[110:113]
	v_mfma_f32_16x16x32_bf16 v[106:109], v[142:145], v[176:179], v[106:109]
	v_mfma_f32_16x16x32_bf16 v[94:97], v[134:137], v[184:187], v[94:97]
	v_mfma_f32_16x16x32_bf16 v[90:93], v[142:145], v[184:187], v[90:93]
	v_mfma_f32_16x16x32_bf16 v[78:81], v[134:137], v[212:215], v[78:81]
	v_mfma_f32_16x16x32_bf16 v[74:77], v[142:145], v[212:215], v[74:77]
	s_setprio 0
	s_setprio 1
	v_mfma_f32_16x16x32_bf16 v[118:121], v[148:151], v[164:167], v[118:121]
	v_mfma_f32_16x16x32_bf16 v[114:117], v[156:159], v[164:167], v[114:117]
	v_mfma_f32_16x16x32_bf16 v[102:105], v[148:151], v[172:175], v[102:105]
	v_mfma_f32_16x16x32_bf16 v[98:101], v[156:159], v[172:175], v[98:101]
	v_mfma_f32_16x16x32_bf16 v[86:89], v[148:151], v[180:183], v[86:89]
	v_mfma_f32_16x16x32_bf16 v[82:85], v[156:159], v[180:183], v[82:85]
	v_mfma_f32_16x16x32_bf16 v[70:73], v[148:151], v[208:211], v[70:73]
	v_mfma_f32_16x16x32_bf16 v[66:69], v[156:159], v[208:211], v[66:69]
	v_mfma_f32_16x16x32_bf16 v[118:121], v[152:155], v[168:171], v[118:121]
	v_mfma_f32_16x16x32_bf16 v[114:117], v[160:163], v[168:171], v[114:117]
	v_mfma_f32_16x16x32_bf16 v[102:105], v[152:155], v[176:179], v[102:105]
	v_mfma_f32_16x16x32_bf16 v[98:101], v[160:163], v[176:179], v[98:101]
	v_mfma_f32_16x16x32_bf16 v[86:89], v[152:155], v[184:187], v[86:89]
	v_mfma_f32_16x16x32_bf16 v[82:85], v[160:163], v[184:187], v[82:85]
	v_mfma_f32_16x16x32_bf16 v[70:73], v[152:155], v[212:215], v[70:73]
	v_mfma_f32_16x16x32_bf16 v[66:69], v[160:163], v[212:215], v[66:69]
	s_setprio 0
	s_barrier
	s_add_u32 s18, s22, 0x158080
	s_addc_u32 s19, s23, 0
	s_add_u32 s22, s22, 0x80
	s_addc_u32 s23, s23, 0
	s_add_i32 s2, s2, s1
	s_mov_b32 m0, s2
	ds_read_b128 v[164:167], v228 offset:49152
	ds_read_b128 v[168:171], v228 offset:50176
	ds_read_b128 v[172:175], v228 offset:51200
	ds_read_b128 v[176:179], v228 offset:52224
	ds_read_b128 v[180:183], v228 offset:53248
	ds_read_b128 v[184:187], v228 offset:54272
	ds_read_b128 v[208:211], v228 offset:55296
	ds_read_b128 v[212:215], v228 offset:56320
	global_load_lds_dwordx4 v0, s[22:23]
	s_add_i32 m0, s2, 0x2000
	s_add_i32 s2, s43, s1
	global_load_lds_dwordx4 v188, s[22:23]
	s_mov_b32 m0, s2
	s_nop 0
	global_load_lds_dwordx4 v0, s[18:19]
	s_add_i32 m0, s2, 0x2000
	s_nop 0
	global_load_lds_dwordx4 v188, s[18:19]
	s_waitcnt vmcnt(6)
	s_waitcnt lgkmcnt(0)
	s_barrier
	s_setprio 1
	s_waitcnt lgkmcnt(0)
	v_mfma_f32_16x16x32_bf16 v[62:65], v[126:129], v[164:167], v[62:65]
	v_mfma_f32_16x16x32_bf16 v[58:61], v[138:141], v[164:167], v[58:61]
	v_mfma_f32_16x16x32_bf16 v[46:49], v[126:129], v[172:175], v[46:49]
	v_mfma_f32_16x16x32_bf16 v[42:45], v[138:141], v[172:175], v[42:45]
	v_mfma_f32_16x16x32_bf16 v[30:33], v[126:129], v[180:183], v[30:33]
	v_mfma_f32_16x16x32_bf16 v[26:29], v[138:141], v[180:183], v[26:29]
	v_mfma_f32_16x16x32_bf16 v[14:17], v[126:129], v[208:211], v[14:17]
	v_mfma_f32_16x16x32_bf16 v[10:13], v[138:141], v[208:211], v[10:13]
	v_mfma_f32_16x16x32_bf16 v[62:65], v[134:137], v[168:171], v[62:65]
	v_mfma_f32_16x16x32_bf16 v[58:61], v[142:145], v[168:171], v[58:61]
	v_mfma_f32_16x16x32_bf16 v[46:49], v[134:137], v[176:179], v[46:49]
	v_mfma_f32_16x16x32_bf16 v[42:45], v[142:145], v[176:179], v[42:45]
	v_mfma_f32_16x16x32_bf16 v[30:33], v[134:137], v[184:187], v[30:33]
	v_mfma_f32_16x16x32_bf16 v[26:29], v[142:145], v[184:187], v[26:29]
	v_mfma_f32_16x16x32_bf16 v[14:17], v[134:137], v[212:215], v[14:17]
	v_mfma_f32_16x16x32_bf16 v[10:13], v[142:145], v[212:215], v[10:13]
	s_setprio 0
	s_setprio 1
	v_mfma_f32_16x16x32_bf16 v[54:57], v[148:151], v[164:167], v[54:57]
	v_mfma_f32_16x16x32_bf16 v[50:53], v[156:159], v[164:167], v[50:53]
	v_mfma_f32_16x16x32_bf16 v[38:41], v[148:151], v[172:175], v[38:41]
	v_mfma_f32_16x16x32_bf16 v[34:37], v[156:159], v[172:175], v[34:37]
	v_mfma_f32_16x16x32_bf16 v[22:25], v[148:151], v[180:183], v[22:25]
	v_mfma_f32_16x16x32_bf16 v[18:21], v[156:159], v[180:183], v[18:21]
	v_mfma_f32_16x16x32_bf16 v[6:9], v[148:151], v[208:211], v[6:9]
	v_mfma_f32_16x16x32_bf16 v[2:5], v[156:159], v[208:211], v[2:5]
	v_mfma_f32_16x16x32_bf16 v[54:57], v[152:155], v[168:171], v[54:57]
	v_mfma_f32_16x16x32_bf16 v[50:53], v[160:163], v[168:171], v[50:53]
	v_mfma_f32_16x16x32_bf16 v[38:41], v[152:155], v[176:179], v[38:41]
	v_mfma_f32_16x16x32_bf16 v[34:37], v[160:163], v[176:179], v[34:37]
	v_mfma_f32_16x16x32_bf16 v[22:25], v[152:155], v[184:187], v[22:25]
	v_mfma_f32_16x16x32_bf16 v[18:21], v[160:163], v[184:187], v[18:21]
	v_mfma_f32_16x16x32_bf16 v[6:9], v[152:155], v[212:215], v[6:9]
	v_mfma_f32_16x16x32_bf16 v[2:5], v[160:163], v[212:215], v[2:5]
	s_setprio 0
	s_barrier
	s_add_i32 s42, s42, 2
	s_add_u32 s40, s40, 0x100
	s_addc_u32 s41, s41, 0
	s_cmpk_gt_u32 s42, 0x53
	s_mov_b64 s[18:19], s[20:21]
	s_cbranch_scc0 .LBB0_281
	s_nop 0
	s_nop 0
	s_nop 0
	s_nop 0
	v_lshl_or_b32 v210, s3, 8, v227
	v_lshl_add_u32 v224, s34, 8, v147
	v_ashrrev_i32_e32 v211, 31, v210
	v_lshlrev_b64 v[126:127], 1, v[210:211]
	v_ashrrev_i32_e32 v225, 31, v224
	v_lshl_add_u64 v[128:129], s[12:13], 0, v[126:127]
	v_lshlrev_b64 v[134:135], 12, v[224:225]
	v_lshl_add_u64 v[136:137], v[128:129], 0, v[134:135]
	global_load_dwordx4 v[240:243], v[136:137], off
	global_load_dwordx4 v[244:247], v[136:137], off offset:256
	v_or_b32_e32 v222, 16, v224
	v_or_b32_e32 v220, 32, v224
	v_or_b32_e32 v218, 48, v224
	v_add_u32_e32 v216, 0x80, v224
	v_add_u32_e32 v214, 0x90, v224
	v_add_u32_e32 v212, 0xa0, v224
	v_add_u32_e32 v208, 0xb0, v224
	v_ashrrev_i32_e32 v223, 31, v222
	v_ashrrev_i32_e32 v221, 31, v220
	v_ashrrev_i32_e32 v219, 31, v218
	v_ashrrev_i32_e32 v217, 31, v216
	v_ashrrev_i32_e32 v215, 31, v214
	v_ashrrev_i32_e32 v213, 31, v212
	v_ashrrev_i32_e32 v209, 31, v208
	v_lshlrev_b64 v[136:137], 12, v[222:223]
	v_lshlrev_b64 v[138:139], 12, v[220:221]
	v_lshlrev_b64 v[140:141], 12, v[218:219]
	v_lshlrev_b64 v[142:143], 12, v[216:217]
	v_lshlrev_b64 v[144:145], 12, v[214:215]
	v_lshlrev_b64 v[148:149], 12, v[212:213]
	v_lshlrev_b64 v[150:151], 12, v[208:209]
	v_lshl_add_u64 v[134:135], s[12:13], 0, v[134:135]
	v_lshl_add_u64 v[136:137], v[128:129], 0, v[136:137]
	v_lshl_add_u64 v[138:139], v[128:129], 0, v[138:139]
	v_lshl_add_u64 v[140:141], v[128:129], 0, v[140:141]
	v_lshl_add_u64 v[142:143], v[128:129], 0, v[142:143]
	v_lshl_add_u64 v[144:145], v[128:129], 0, v[144:145]
	v_lshl_add_u64 v[248:249], v[128:129], 0, v[148:149]
	v_lshl_add_u64 v[128:129], v[128:129], 0, v[150:151]
	v_lshl_add_u64 v[250:251], v[134:135], 0, v[126:127]
	global_load_dwordx4 v[184:187], v[136:137], off
	global_load_dwordx4 v[180:183], v[136:137], off offset:256
	global_load_dwordx4 v[176:179], v[138:139], off
	global_load_dwordx4 v[172:175], v[138:139], off offset:256
	global_load_dwordx4 v[168:171], v[140:141], off
	global_load_dwordx4 v[164:167], v[140:141], off offset:256
	global_load_dwordx4 v[160:163], v[142:143], off
	global_load_dwordx4 v[156:159], v[142:143], off offset:256
	global_load_dwordx4 v[152:155], v[144:145], off
	global_load_dwordx4 v[148:151], v[144:145], off offset:256
	s_nop 0
	global_load_dwordx4 v[142:145], v[248:249], off
	global_load_dwordx4 v[138:141], v[248:249], off offset:256
	global_load_dwordx4 v[134:137], v[128:129], off
	s_nop 0
	global_load_dwordx4 v[126:129], v[128:129], off offset:256
	s_lshl_b32 s18, s3, 2
	s_ashr_i32 s19, s18, 31
	s_waitcnt vmcnt(0)
	v_lshlrev_b32_e32 v248, 16, v240
	v_and_b32_e32 v249, 0xffff0000, v240
	v_lshlrev_b32_e32 v240, 16, v241
	v_and_b32_e32 v241, 0xffff0000, v241
	v_lshlrev_b32_e32 v252, 16, v242
	v_and_b32_e32 v253, 0xffff0000, v242
	v_lshlrev_b32_e32 v242, 16, v243
	v_and_b32_e32 v243, 0xffff0000, v243
	v_pk_fma_f32 v[132:133], v[132:133], 0.5, v[240:241] op_sel_hi:[1,0,1]
	v_pk_fma_f32 v[240:241], v[124:125], 0.5, v[242:243] op_sel_hi:[1,0,1]
	v_pk_fma_f32 v[124:125], v[122:123], 0.5, v[252:253] op_sel_hi:[1,0,1]
	v_pk_fma_f32 v[130:131], v[130:131], 0.5, v[248:249] op_sel_hi:[1,0,1]
	v_lshlrev_b32_e32 v236, 16, v244
	v_cvt_pk_bf16_f32 v122, v130, v131
	v_cvt_pk_bf16_f32 v123, v132, v133
	v_cvt_pk_bf16_f32 v124, v124, v125
	v_cvt_pk_bf16_f32 v125, v240, v241
	global_store_dwordx4 v[250:251], v[122:125], off
	v_lshlrev_b32_e32 v130, 16, v122
	v_lshlrev_b32_e32 v131, 16, v123
	v_and_b32_e32 v122, 0xffff0000, v122
	v_and_b32_e32 v123, 0xffff0000, v123
	v_lshlrev_b32_e32 v132, 16, v124
	v_and_b32_e32 v124, 0xffff0000, v124
	v_lshlrev_b32_e32 v133, 16, v125
	v_and_b32_e32 v125, 0xffff0000, v125
	v_mul_f32_e32 v122, v122, v122
	v_mul_f32_e32 v123, v123, v123
	v_mul_f32_e32 v124, v124, v124
	v_mul_f32_e32 v125, v125, v125
	v_fmac_f32_e32 v122, v130, v130
	v_fmac_f32_e32 v123, v131, v131
	v_fmac_f32_e32 v124, v132, v132
	v_fmac_f32_e32 v125, v133, v133
	v_add_f32_e32 v122, v122, v123
	v_add_f32_e32 v123, v124, v125
	v_and_b32_e32 v237, 0xffff0000, v244
	v_add_f32_e32 v132, v122, v123
	v_lshlrev_b32_e32 v122, 16, v245
	v_and_b32_e32 v123, 0xffff0000, v245
	v_lshlrev_b32_e32 v124, 16, v246
	v_and_b32_e32 v125, 0xffff0000, v246
	v_lshlrev_b32_e32 v130, 16, v247
	v_and_b32_e32 v131, 0xffff0000, v247
	v_pk_fma_f32 v[120:121], v[120:121], 0.5, v[122:123] op_sel_hi:[1,0,1]
	v_pk_fma_f32 v[118:119], v[118:119], 0.5, v[236:237] op_sel_hi:[1,0,1]
	v_pk_fma_f32 v[122:123], v[116:117], 0.5, v[130:131] op_sel_hi:[1,0,1]
	v_pk_fma_f32 v[116:117], v[114:115], 0.5, v[124:125] op_sel_hi:[1,0,1]
	v_cvt_pk_bf16_f32 v114, v118, v119
	v_cvt_pk_bf16_f32 v115, v120, v121
	s_nop 0
	v_cvt_pk_bf16_f32 v116, v116, v117
	v_cvt_pk_bf16_f32 v117, v122, v123
	global_store_dwordx4 v[250:251], v[114:117], off offset:256
	v_lshlrev_b32_e32 v118, 16, v114
	v_lshlrev_b32_e32 v119, 16, v115
	v_and_b32_e32 v114, 0xffff0000, v114
	v_and_b32_e32 v115, 0xffff0000, v115
	v_mul_f32_e32 v114, v114, v114
	v_mul_f32_e32 v115, v115, v115
	v_lshlrev_b32_e32 v120, 16, v116
	v_and_b32_e32 v116, 0xffff0000, v116
	v_lshlrev_b32_e32 v121, 16, v117
	v_and_b32_e32 v117, 0xffff0000, v117
	v_fmac_f32_e32 v114, v118, v118
	v_fmac_f32_e32 v115, v119, v119
	v_add_f32_e32 v114, v114, v115
	v_mul_f32_e32 v115, v116, v116
	v_mul_f32_e32 v116, v117, v117
	v_fmac_f32_e32 v115, v120, v120
	v_fmac_f32_e32 v116, v121, v121
	v_add_f32_e32 v115, v115, v116
	v_add_f32_e32 v114, v114, v115
	s_mov_b32 s2, 0
	v_add_f32_e32 v114, v132, v114
	v_mbcnt_lo_u32_b32 v115, -1, s2
	v_mbcnt_hi_u32_b32 v115, -1, v115
	v_lshlrev_b32_e32 v115, 2, v115
	v_xor_b32_e32 v115, 64, v115
	ds_bpermute_b32 v115, v115, v114
	s_mov_b32 s2, 0
	s_waitcnt lgkmcnt(0)
	v_add_f32_e32 v114, v114, v115
	v_mbcnt_lo_u32_b32 v115, -1, s2
	v_mbcnt_hi_u32_b32 v115, -1, v115
	v_lshlrev_b32_e32 v115, 2, v115
	v_xor_b32_e32 v115, 0x80, v115
	ds_bpermute_b32 v115, v115, v114
	s_and_saveexec_b64 s[20:21], s[6:7]
	s_cbranch_execz .LBB0_284
	v_lshlrev_b64 v[116:117], 7, v[224:225]
	v_lshl_add_u64 v[116:117], s[14:15], 0, v[116:117]
	v_lshl_add_u64 v[116:117], s[18:19], 2, v[116:117]
	s_lshl_b32 s50, s35, 2
	v_lshl_add_u64 v[116:117], v[116:117], 0, s[50:51]
	s_waitcnt lgkmcnt(0)
	v_add_f32_e32 v114, v114, v115
	global_store_dword v[116:117], v114, off

.LBB0_322:
	s_add_u32 s22, s20, 0x100
	s_addc_u32 s23, s21, 0
	s_add_i32 s2, 0, 0x10000
	s_cmpk_eq_i32 s42, 0x52
	s_cselect_b32 s27, s9, s23
	s_cselect_b32 s26, s8, s22
	s_cselect_b32 s25, s19, s41
	s_cselect_b32 s24, s18, s40
	s_add_u32 s100, s20, 0xffea8000
	s_addc_u32 s101, s21, -1
	s_add_i32 s43, 0, 0x14000
	v_add_u32_e32 v142, s2, v240
	v_add_u32_e32 v160, s43, v240
	ds_read_b128 v[130:133], v142
	ds_read_b128 v[134:137], v142 offset:1024
	ds_read_b128 v[138:141], v142 offset:2048
	ds_read_b128 v[142:145], v142 offset:3072
	ds_read_b128 v[148:151], v160
	ds_read_b128 v[152:155], v160 offset:1024
	ds_read_b128 v[156:159], v160 offset:2048
	ds_read_b128 v[160:163], v160 offset:3072
	s_add_i32 m0, s1, 0xc000
	ds_read_b128 v[164:167], v242
	ds_read_b128 v[168:171], v242 offset:1024
	ds_read_b128 v[172:175], v242 offset:2048
	ds_read_b128 v[176:179], v242 offset:3072
	ds_read_b128 v[180:183], v242 offset:4096
	ds_read_b128 v[184:187], v242 offset:5120
	ds_read_b128 v[188:191], v242 offset:6144
	ds_read_b128 v[212:215], v242 offset:7168
	s_mov_b32 m0, s35
	s_nop 0
	global_load_lds_dwordx4 v208, s[100:101]
	s_mov_b32 m0, s36
	s_nop 0
	global_load_lds_dwordx4 v210, s[100:101]
	s_add_i32 m0, s1, 0xc000
	s_nop 0
	global_load_lds_dwordx4 v208, s[20:21]
	s_add_i32 m0, s1, 0xe000
	s_nop 0
	global_load_lds_dwordx4 v210, s[20:21]
	s_waitcnt vmcnt(8)
	s_waitcnt lgkmcnt(0)
	s_barrier
	s_setprio 1
	s_waitcnt lgkmcnt(0)
	v_mfma_f32_16x16x32_bf16 v[126:129], v[130:133], v[164:167], v[126:129]
	v_mfma_f32_16x16x32_bf16 v[122:125], v[138:141], v[164:167], v[122:125]
	v_mfma_f32_16x16x32_bf16 v[110:113], v[130:133], v[172:175], v[110:113]
	v_mfma_f32_16x16x32_bf16 v[106:109], v[138:141], v[172:175], v[106:109]
	v_mfma_f32_16x16x32_bf16 v[94:97], v[130:133], v[180:183], v[94:97]
	v_mfma_f32_16x16x32_bf16 v[90:93], v[138:141], v[180:183], v[90:93]
	v_mfma_f32_16x16x32_bf16 v[78:81], v[130:133], v[188:191], v[78:81]
	v_mfma_f32_16x16x32_bf16 v[74:77], v[138:141], v[188:191], v[74:77]
	v_mfma_f32_16x16x32_bf16 v[126:129], v[134:137], v[168:171], v[126:129]
	v_mfma_f32_16x16x32_bf16 v[122:125], v[142:145], v[168:171], v[122:125]
	v_mfma_f32_16x16x32_bf16 v[110:113], v[134:137], v[176:179], v[110:113]
	v_mfma_f32_16x16x32_bf16 v[106:109], v[142:145], v[176:179], v[106:109]
	v_mfma_f32_16x16x32_bf16 v[94:97], v[134:137], v[184:187], v[94:97]
	v_mfma_f32_16x16x32_bf16 v[90:93], v[142:145], v[184:187], v[90:93]
	v_mfma_f32_16x16x32_bf16 v[78:81], v[134:137], v[212:215], v[78:81]
	v_mfma_f32_16x16x32_bf16 v[74:77], v[142:145], v[212:215], v[74:77]
	s_setprio 0
	s_setprio 1
	v_mfma_f32_16x16x32_bf16 v[118:121], v[148:151], v[164:167], v[118:121]
	v_mfma_f32_16x16x32_bf16 v[114:117], v[156:159], v[164:167], v[114:117]
	v_mfma_f32_16x16x32_bf16 v[102:105], v[148:151], v[172:175], v[102:105]
	v_mfma_f32_16x16x32_bf16 v[98:101], v[156:159], v[172:175], v[98:101]
	v_mfma_f32_16x16x32_bf16 v[86:89], v[148:151], v[180:183], v[86:89]
	v_mfma_f32_16x16x32_bf16 v[82:85], v[156:159], v[180:183], v[82:85]
	v_mfma_f32_16x16x32_bf16 v[70:73], v[148:151], v[188:191], v[70:73]
	v_mfma_f32_16x16x32_bf16 v[66:69], v[156:159], v[188:191], v[66:69]
	v_mfma_f32_16x16x32_bf16 v[118:121], v[152:155], v[168:171], v[118:121]
	v_mfma_f32_16x16x32_bf16 v[114:117], v[160:163], v[168:171], v[114:117]
	v_mfma_f32_16x16x32_bf16 v[102:105], v[152:155], v[176:179], v[102:105]
	v_mfma_f32_16x16x32_bf16 v[98:101], v[160:163], v[176:179], v[98:101]
	v_mfma_f32_16x16x32_bf16 v[86:89], v[152:155], v[184:187], v[86:89]
	v_mfma_f32_16x16x32_bf16 v[82:85], v[160:163], v[184:187], v[82:85]
	v_mfma_f32_16x16x32_bf16 v[70:73], v[152:155], v[212:215], v[70:73]
	v_mfma_f32_16x16x32_bf16 v[66:69], v[160:163], v[212:215], v[66:69]
	s_setprio 0
	s_barrier
	s_add_u32 s20, s24, 0x158000
	s_addc_u32 s21, s25, 0
	s_add_i32 s2, s2, s0
	s_mov_b32 m0, s2
	ds_read_b128 v[164:167], v242 offset:16384
	ds_read_b128 v[168:171], v242 offset:17408
	ds_read_b128 v[172:175], v242 offset:18432
	ds_read_b128 v[176:179], v242 offset:19456
	ds_read_b128 v[180:183], v242 offset:20480
	ds_read_b128 v[184:187], v242 offset:21504
	ds_read_b128 v[188:191], v242 offset:22528
	ds_read_b128 v[212:215], v242 offset:23552
	global_load_lds_dwordx4 v0, s[24:25]
	s_add_i32 m0, s2, 0x2000
	s_add_i32 s2, s43, s0
	global_load_lds_dwordx4 v192, s[24:25]
	s_mov_b32 m0, s2
	s_nop 0
	global_load_lds_dwordx4 v0, s[20:21]
	s_add_i32 m0, s2, 0x2000
	s_nop 0
	global_load_lds_dwordx4 v192, s[20:21]
	s_waitcnt vmcnt(6)
	s_waitcnt lgkmcnt(0)
	s_barrier
	s_setprio 1
	s_waitcnt lgkmcnt(0)
	v_mfma_f32_16x16x32_bf16 v[62:65], v[130:133], v[164:167], v[62:65]
	v_mfma_f32_16x16x32_bf16 v[58:61], v[138:141], v[164:167], v[58:61]
	v_mfma_f32_16x16x32_bf16 v[46:49], v[130:133], v[172:175], v[46:49]
	v_mfma_f32_16x16x32_bf16 v[42:45], v[138:141], v[172:175], v[42:45]
	v_mfma_f32_16x16x32_bf16 v[30:33], v[130:133], v[180:183], v[30:33]
	v_mfma_f32_16x16x32_bf16 v[26:29], v[138:141], v[180:183], v[26:29]
	v_mfma_f32_16x16x32_bf16 v[14:17], v[130:133], v[188:191], v[14:17]
	v_mfma_f32_16x16x32_bf16 v[10:13], v[138:141], v[188:191], v[10:13]
	v_mfma_f32_16x16x32_bf16 v[62:65], v[134:137], v[168:171], v[62:65]
	v_mfma_f32_16x16x32_bf16 v[58:61], v[142:145], v[168:171], v[58:61]
	v_mfma_f32_16x16x32_bf16 v[46:49], v[134:137], v[176:179], v[46:49]
	v_mfma_f32_16x16x32_bf16 v[42:45], v[142:145], v[176:179], v[42:45]
	v_mfma_f32_16x16x32_bf16 v[30:33], v[134:137], v[184:187], v[30:33]
	v_mfma_f32_16x16x32_bf16 v[26:29], v[142:145], v[184:187], v[26:29]
	v_mfma_f32_16x16x32_bf16 v[14:17], v[134:137], v[212:215], v[14:17]
	v_mfma_f32_16x16x32_bf16 v[10:13], v[142:145], v[212:215], v[10:13]
	s_setprio 0
	s_setprio 1
	v_mfma_f32_16x16x32_bf16 v[54:57], v[148:151], v[164:167], v[54:57]
	v_mfma_f32_16x16x32_bf16 v[50:53], v[156:159], v[164:167], v[50:53]
	v_mfma_f32_16x16x32_bf16 v[38:41], v[148:151], v[172:175], v[38:41]
	v_mfma_f32_16x16x32_bf16 v[34:37], v[156:159], v[172:175], v[34:37]
	v_mfma_f32_16x16x32_bf16 v[22:25], v[148:151], v[180:183], v[22:25]
	v_mfma_f32_16x16x32_bf16 v[18:21], v[156:159], v[180:183], v[18:21]
	v_mfma_f32_16x16x32_bf16 v[6:9], v[148:151], v[188:191], v[6:9]
	v_mfma_f32_16x16x32_bf16 v[2:5], v[156:159], v[188:191], v[2:5]
	v_mfma_f32_16x16x32_bf16 v[54:57], v[152:155], v[168:171], v[54:57]
	v_mfma_f32_16x16x32_bf16 v[50:53], v[160:163], v[168:171], v[50:53]
	v_mfma_f32_16x16x32_bf16 v[38:41], v[152:155], v[176:179], v[38:41]
	v_mfma_f32_16x16x32_bf16 v[34:37], v[160:163], v[176:179], v[34:37]
	v_mfma_f32_16x16x32_bf16 v[22:25], v[152:155], v[184:187], v[22:25]
	v_mfma_f32_16x16x32_bf16 v[18:21], v[160:163], v[184:187], v[18:21]
	v_mfma_f32_16x16x32_bf16 v[6:9], v[152:155], v[212:215], v[6:9]
	v_mfma_f32_16x16x32_bf16 v[2:5], v[160:163], v[212:215], v[2:5]
	s_setprio 0
	s_barrier
	s_add_u32 s20, s26, 0x158000
	s_addc_u32 s21, s27, 0
	s_add_i32 s2, 0, 0x18000
	s_add_i32 s43, 0, 0x1c000
	v_add_u32_e32 v142, s2, v240
	v_add_u32_e32 v160, s43, v240
	ds_read_b128 v[130:133], v142
	ds_read_b128 v[134:137], v142 offset:1024
	ds_read_b128 v[138:141], v142 offset:2048
	ds_read_b128 v[142:145], v142 offset:3072
	ds_read_b128 v[148:151], v160
	ds_read_b128 v[152:155], v160 offset:1024
	ds_read_b128 v[156:159], v160 offset:2048
	ds_read_b128 v[160:163], v160 offset:3072
	s_mov_b32 m0, s31
	ds_read_b128 v[164:167], v242 offset:32768
	ds_read_b128 v[168:171], v242 offset:33792
	ds_read_b128 v[172:175], v242 offset:34816
	ds_read_b128 v[176:179], v242 offset:35840
	ds_read_b128 v[180:183], v242 offset:36864
	ds_read_b128 v[184:187], v242 offset:37888
	ds_read_b128 v[188:191], v242 offset:38912
	ds_read_b128 v[212:215], v242 offset:39936
	s_mov_b32 m0, s1
	s_nop 0
	global_load_lds_dwordx4 v206, s[26:27]
	s_mov_b32 m0, s30
	s_nop 0
	global_load_lds_dwordx4 v194, s[26:27]
	s_mov_b32 m0, s31
	s_nop 0
	global_load_lds_dwordx4 v206, s[20:21]
	s_mov_b32 m0, s33
	s_nop 0
	global_load_lds_dwordx4 v194, s[20:21]
	s_waitcnt vmcnt(8)
	s_waitcnt lgkmcnt(0)
	s_barrier
	s_setprio 1
	s_waitcnt lgkmcnt(0)
	v_mfma_f32_16x16x32_bf16 v[126:129], v[130:133], v[164:167], v[126:129]
	v_mfma_f32_16x16x32_bf16 v[122:125], v[138:141], v[164:167], v[122:125]
	v_mfma_f32_16x16x32_bf16 v[110:113], v[130:133], v[172:175], v[110:113]
	v_mfma_f32_16x16x32_bf16 v[106:109], v[138:141], v[172:175], v[106:109]
	v_mfma_f32_16x16x32_bf16 v[94:97], v[130:133], v[180:183], v[94:97]
	v_mfma_f32_16x16x32_bf16 v[90:93], v[138:141], v[180:183], v[90:93]
	v_mfma_f32_16x16x32_bf16 v[78:81], v[130:133], v[188:191], v[78:81]
	v_mfma_f32_16x16x32_bf16 v[74:77], v[138:141], v[188:191], v[74:77]
	v_mfma_f32_16x16x32_bf16 v[126:129], v[134:137], v[168:171], v[126:129]
	v_mfma_f32_16x16x32_bf16 v[122:125], v[142:145], v[168:171], v[122:125]
	v_mfma_f32_16x16x32_bf16 v[110:113], v[134:137], v[176:179], v[110:113]
	v_mfma_f32_16x16x32_bf16 v[106:109], v[142:145], v[176:179], v[106:109]
	v_mfma_f32_16x16x32_bf16 v[94:97], v[134:137], v[184:187], v[94:97]
	v_mfma_f32_16x16x32_bf16 v[90:93], v[142:145], v[184:187], v[90:93]
	v_mfma_f32_16x16x32_bf16 v[78:81], v[134:137], v[212:215], v[78:81]
	v_mfma_f32_16x16x32_bf16 v[74:77], v[142:145], v[212:215], v[74:77]
	s_setprio 0
	s_setprio 1
	v_mfma_f32_16x16x32_bf16 v[118:121], v[148:151], v[164:167], v[118:121]
	v_mfma_f32_16x16x32_bf16 v[114:117], v[156:159], v[164:167], v[114:117]
	v_mfma_f32_16x16x32_bf16 v[102:105], v[148:151], v[172:175], v[102:105]
	v_mfma_f32_16x16x32_bf16 v[98:101], v[156:159], v[172:175], v[98:101]
	v_mfma_f32_16x16x32_bf16 v[86:89], v[148:151], v[180:183], v[86:89]
	v_mfma_f32_16x16x32_bf16 v[82:85], v[156:159], v[180:183], v[82:85]
	v_mfma_f32_16x16x32_bf16 v[70:73], v[148:151], v[188:191], v[70:73]
	v_mfma_f32_16x16x32_bf16 v[66:69], v[156:159], v[188:191], v[66:69]
	v_mfma_f32_16x16x32_bf16 v[118:121], v[152:155], v[168:171], v[118:121]
	v_mfma_f32_16x16x32_bf16 v[114:117], v[160:163], v[168:171], v[114:117]
	v_mfma_f32_16x16x32_bf16 v[102:105], v[152:155], v[176:179], v[102:105]
	v_mfma_f32_16x16x32_bf16 v[98:101], v[160:163], v[176:179], v[98:101]
	v_mfma_f32_16x16x32_bf16 v[86:89], v[152:155], v[184:187], v[86:89]
	v_mfma_f32_16x16x32_bf16 v[82:85], v[160:163], v[184:187], v[82:85]
	v_mfma_f32_16x16x32_bf16 v[70:73], v[152:155], v[212:215], v[70:73]
	v_mfma_f32_16x16x32_bf16 v[66:69], v[160:163], v[212:215], v[66:69]
	s_setprio 0
	s_barrier
	s_add_u32 s20, s24, 0x158080
	s_addc_u32 s21, s25, 0
	s_add_u32 s24, s24, 0x80
	s_addc_u32 s25, s25, 0
	s_add_i32 s2, s2, s0
	s_mov_b32 m0, s2
	ds_read_b128 v[164:167], v242 offset:49152
	ds_read_b128 v[168:171], v242 offset:50176
	ds_read_b128 v[172:175], v242 offset:51200
	ds_read_b128 v[176:179], v242 offset:52224
	ds_read_b128 v[180:183], v242 offset:53248
	ds_read_b128 v[184:187], v242 offset:54272
	ds_read_b128 v[188:191], v242 offset:55296
	ds_read_b128 v[212:215], v242 offset:56320
	global_load_lds_dwordx4 v0, s[24:25]
	s_add_i32 m0, s2, 0x2000
	s_add_i32 s2, s43, s0
	global_load_lds_dwordx4 v192, s[24:25]
	s_mov_b32 m0, s2
	s_nop 0
	global_load_lds_dwordx4 v0, s[20:21]
	s_add_i32 m0, s2, 0x2000
	s_nop 0
	global_load_lds_dwordx4 v192, s[20:21]
	s_waitcnt vmcnt(6)
	s_waitcnt lgkmcnt(0)
	s_barrier
	s_setprio 1
	s_waitcnt lgkmcnt(0)
	v_mfma_f32_16x16x32_bf16 v[62:65], v[130:133], v[164:167], v[62:65]
	v_mfma_f32_16x16x32_bf16 v[58:61], v[138:141], v[164:167], v[58:61]
	v_mfma_f32_16x16x32_bf16 v[46:49], v[130:133], v[172:175], v[46:49]
	v_mfma_f32_16x16x32_bf16 v[42:45], v[138:141], v[172:175], v[42:45]
	v_mfma_f32_16x16x32_bf16 v[30:33], v[130:133], v[180:183], v[30:33]
	v_mfma_f32_16x16x32_bf16 v[26:29], v[138:141], v[180:183], v[26:29]
	v_mfma_f32_16x16x32_bf16 v[14:17], v[130:133], v[188:191], v[14:17]
	v_mfma_f32_16x16x32_bf16 v[10:13], v[138:141], v[188:191], v[10:13]
	v_mfma_f32_16x16x32_bf16 v[62:65], v[134:137], v[168:171], v[62:65]
	v_mfma_f32_16x16x32_bf16 v[58:61], v[142:145], v[168:171], v[58:61]
	v_mfma_f32_16x16x32_bf16 v[46:49], v[134:137], v[176:179], v[46:49]
	v_mfma_f32_16x16x32_bf16 v[42:45], v[142:145], v[176:179], v[42:45]
	v_mfma_f32_16x16x32_bf16 v[30:33], v[134:137], v[184:187], v[30:33]
	v_mfma_f32_16x16x32_bf16 v[26:29], v[142:145], v[184:187], v[26:29]
	v_mfma_f32_16x16x32_bf16 v[14:17], v[134:137], v[212:215], v[14:17]
	v_mfma_f32_16x16x32_bf16 v[10:13], v[142:145], v[212:215], v[10:13]
	s_setprio 0
	s_setprio 1
	v_mfma_f32_16x16x32_bf16 v[54:57], v[148:151], v[164:167], v[54:57]
	v_mfma_f32_16x16x32_bf16 v[50:53], v[156:159], v[164:167], v[50:53]
	v_mfma_f32_16x16x32_bf16 v[38:41], v[148:151], v[172:175], v[38:41]
	v_mfma_f32_16x16x32_bf16 v[34:37], v[156:159], v[172:175], v[34:37]
	v_mfma_f32_16x16x32_bf16 v[22:25], v[148:151], v[180:183], v[22:25]
	v_mfma_f32_16x16x32_bf16 v[18:21], v[156:159], v[180:183], v[18:21]
	v_mfma_f32_16x16x32_bf16 v[6:9], v[148:151], v[188:191], v[6:9]
	v_mfma_f32_16x16x32_bf16 v[2:5], v[156:159], v[188:191], v[2:5]
	v_mfma_f32_16x16x32_bf16 v[54:57], v[152:155], v[168:171], v[54:57]
	v_mfma_f32_16x16x32_bf16 v[50:53], v[160:163], v[168:171], v[50:53]
	v_mfma_f32_16x16x32_bf16 v[38:41], v[152:155], v[176:179], v[38:41]
	v_mfma_f32_16x16x32_bf16 v[34:37], v[160:163], v[176:179], v[34:37]
	v_mfma_f32_16x16x32_bf16 v[22:25], v[152:155], v[184:187], v[22:25]
	v_mfma_f32_16x16x32_bf16 v[18:21], v[160:163], v[184:187], v[18:21]
	v_mfma_f32_16x16x32_bf16 v[6:9], v[152:155], v[212:215], v[6:9]
	v_mfma_f32_16x16x32_bf16 v[2:5], v[160:163], v[212:215], v[2:5]
	s_setprio 0
	s_barrier
	s_add_i32 s42, s42, 2
	s_add_u32 s40, s40, 0x100
	s_addc_u32 s41, s41, 0
	s_cmpk_gt_u32 s42, 0x53
	s_mov_b64 s[20:21], s[22:23]
	s_cbranch_scc0 .LBB0_322
	s_nop 0
	s_nop 0
	s_nop 0
	s_nop 0
	s_and_b64 vcc, exec, s[16:17]
	s_cbranch_vccz .LBB0_325
	s_barrier

.LBB0_408:
	s_add_u32 s2, s24, 0xfff80080
	s_addc_u32 s22, s25, -1
	s_add_i32 s45, 0, 0x10000
	s_cmp_eq_u32 s44, 28
	s_cselect_b32 s27, s17, s22
	s_cselect_b32 s26, s40, s2
	v_add_u32_e32 v144, s45, v148
	s_cselect_b32 s23, s15, s43
	s_cselect_b32 s22, s41, s42
	s_add_u32 s100, s24, 0xfff80000
	s_addc_u32 s101, s25, -1
	s_add_i32 s2, 0, 0x14000
	ds_read_b128 v[140:143], v144
	ds_read_b128 v[152:155], v144 offset:1024
	ds_read_b128 v[156:159], v144 offset:2048
	ds_read_b128 v[160:163], v144 offset:3072
	v_add_u32_e32 v144, s2, v148
	ds_read_b128 v[164:167], v144
	ds_read_b128 v[168:171], v144 offset:1024
	ds_read_b128 v[172:175], v144 offset:2048
	ds_read_b128 v[176:179], v144 offset:3072
	s_add_i32 m0, s29, 0xc000
	ds_read_b128 v[180:183], v151
	ds_read_b128 v[184:187], v151 offset:1024
	ds_read_b128 v[188:191], v151 offset:2048
	ds_read_b128 v[192:195], v151 offset:3072
	ds_read_b128 v[206:209], v151 offset:4096
	ds_read_b128 v[210:213], v151 offset:5120
	ds_read_b128 v[214:217], v151 offset:6144
	ds_read_b128 v[218:221], v151 offset:7168
	s_mov_b32 m0, s35
	s_nop 0
	global_load_lds_dwordx4 v136, s[100:101]
	s_mov_b32 m0, s36
	s_nop 0
	global_load_lds_dwordx4 v138, s[100:101]
	s_add_i32 m0, s29, 0xc000
	s_nop 0
	global_load_lds_dwordx4 v136, s[24:25]
	s_add_i32 m0, s29, 0xe000
	s_nop 0
	global_load_lds_dwordx4 v138, s[24:25]
	s_waitcnt vmcnt(8)
	s_waitcnt lgkmcnt(0)
	s_barrier
	s_setprio 1
	s_waitcnt lgkmcnt(0)
	v_mfma_f32_16x16x32_bf16 v[126:129], v[140:143], v[180:183], v[126:129]
	v_mfma_f32_16x16x32_bf16 v[122:125], v[156:159], v[180:183], v[122:125]
	v_mfma_f32_16x16x32_bf16 v[110:113], v[140:143], v[188:191], v[110:113]
	v_mfma_f32_16x16x32_bf16 v[106:109], v[156:159], v[188:191], v[106:109]
	v_mfma_f32_16x16x32_bf16 v[94:97], v[140:143], v[206:209], v[94:97]
	v_mfma_f32_16x16x32_bf16 v[90:93], v[156:159], v[206:209], v[90:93]
	v_mfma_f32_16x16x32_bf16 v[78:81], v[140:143], v[214:217], v[78:81]
	v_mfma_f32_16x16x32_bf16 v[74:77], v[156:159], v[214:217], v[74:77]
	v_mfma_f32_16x16x32_bf16 v[126:129], v[152:155], v[184:187], v[126:129]
	v_mfma_f32_16x16x32_bf16 v[122:125], v[160:163], v[184:187], v[122:125]
	v_mfma_f32_16x16x32_bf16 v[110:113], v[152:155], v[192:195], v[110:113]
	v_mfma_f32_16x16x32_bf16 v[106:109], v[160:163], v[192:195], v[106:109]
	v_mfma_f32_16x16x32_bf16 v[94:97], v[152:155], v[210:213], v[94:97]
	v_mfma_f32_16x16x32_bf16 v[90:93], v[160:163], v[210:213], v[90:93]
	v_mfma_f32_16x16x32_bf16 v[78:81], v[152:155], v[218:221], v[78:81]
	v_mfma_f32_16x16x32_bf16 v[74:77], v[160:163], v[218:221], v[74:77]
	s_setprio 0
	s_setprio 1
	v_mfma_f32_16x16x32_bf16 v[118:121], v[164:167], v[180:183], v[118:121]
	v_mfma_f32_16x16x32_bf16 v[114:117], v[172:175], v[180:183], v[114:117]
	v_mfma_f32_16x16x32_bf16 v[102:105], v[164:167], v[188:191], v[102:105]
	v_mfma_f32_16x16x32_bf16 v[98:101], v[172:175], v[188:191], v[98:101]
	v_mfma_f32_16x16x32_bf16 v[86:89], v[164:167], v[206:209], v[86:89]
	v_mfma_f32_16x16x32_bf16 v[82:85], v[172:175], v[206:209], v[82:85]
	v_mfma_f32_16x16x32_bf16 v[70:73], v[164:167], v[214:217], v[70:73]
	v_mfma_f32_16x16x32_bf16 v[66:69], v[172:175], v[214:217], v[66:69]
	v_mfma_f32_16x16x32_bf16 v[118:121], v[168:171], v[184:187], v[118:121]
	v_mfma_f32_16x16x32_bf16 v[114:117], v[176:179], v[184:187], v[114:117]
	v_mfma_f32_16x16x32_bf16 v[102:105], v[168:171], v[192:195], v[102:105]
	v_mfma_f32_16x16x32_bf16 v[98:101], v[176:179], v[192:195], v[98:101]
	v_mfma_f32_16x16x32_bf16 v[86:89], v[168:171], v[210:213], v[86:89]
	v_mfma_f32_16x16x32_bf16 v[82:85], v[176:179], v[210:213], v[82:85]
	v_mfma_f32_16x16x32_bf16 v[70:73], v[168:171], v[218:221], v[70:73]
	v_mfma_f32_16x16x32_bf16 v[66:69], v[176:179], v[218:221], v[66:69]
	s_setprio 0
	s_barrier
	s_add_u32 s46, s22, 0x80000
	s_addc_u32 s47, s23, 0
	s_add_i32 s45, s45, s28
	s_mov_b32 m0, s45
	ds_read_b128 v[180:183], v151 offset:16384
	ds_read_b128 v[184:187], v151 offset:17408
	ds_read_b128 v[188:191], v151 offset:18432
	ds_read_b128 v[192:195], v151 offset:19456
	ds_read_b128 v[206:209], v151 offset:20480
	ds_read_b128 v[210:213], v151 offset:21504
	ds_read_b128 v[214:217], v151 offset:22528
	ds_read_b128 v[218:221], v151 offset:23552
	global_load_lds_dwordx4 v0, s[22:23]
	s_add_i32 m0, s45, 0x2000
	s_add_i32 s2, s2, s28
	global_load_lds_dwordx4 v130, s[22:23]
	s_mov_b32 m0, s2
	s_nop 0
	global_load_lds_dwordx4 v0, s[46:47]
	s_add_i32 m0, s2, 0x2000
	s_nop 0
	global_load_lds_dwordx4 v130, s[46:47]
	s_waitcnt vmcnt(6)
	s_waitcnt lgkmcnt(0)
	s_barrier
	s_setprio 1
	s_waitcnt lgkmcnt(0)
	v_mfma_f32_16x16x32_bf16 v[62:65], v[140:143], v[180:183], v[62:65]
	v_mfma_f32_16x16x32_bf16 v[58:61], v[156:159], v[180:183], v[58:61]
	v_mfma_f32_16x16x32_bf16 v[46:49], v[140:143], v[188:191], v[46:49]
	v_mfma_f32_16x16x32_bf16 v[42:45], v[156:159], v[188:191], v[42:45]
	v_mfma_f32_16x16x32_bf16 v[30:33], v[140:143], v[206:209], v[30:33]
	v_mfma_f32_16x16x32_bf16 v[26:29], v[156:159], v[206:209], v[26:29]
	v_mfma_f32_16x16x32_bf16 v[14:17], v[140:143], v[214:217], v[14:17]
	v_mfma_f32_16x16x32_bf16 v[10:13], v[156:159], v[214:217], v[10:13]
	v_mfma_f32_16x16x32_bf16 v[62:65], v[152:155], v[184:187], v[62:65]
	v_mfma_f32_16x16x32_bf16 v[58:61], v[160:163], v[184:187], v[58:61]
	v_mfma_f32_16x16x32_bf16 v[46:49], v[152:155], v[192:195], v[46:49]
	v_mfma_f32_16x16x32_bf16 v[42:45], v[160:163], v[192:195], v[42:45]
	v_mfma_f32_16x16x32_bf16 v[30:33], v[152:155], v[210:213], v[30:33]
	v_mfma_f32_16x16x32_bf16 v[26:29], v[160:163], v[210:213], v[26:29]
	v_mfma_f32_16x16x32_bf16 v[14:17], v[152:155], v[218:221], v[14:17]
	v_mfma_f32_16x16x32_bf16 v[10:13], v[160:163], v[218:221], v[10:13]
	s_setprio 0
	s_setprio 1
	v_mfma_f32_16x16x32_bf16 v[54:57], v[164:167], v[180:183], v[54:57]
	v_mfma_f32_16x16x32_bf16 v[50:53], v[172:175], v[180:183], v[50:53]
	v_mfma_f32_16x16x32_bf16 v[38:41], v[164:167], v[188:191], v[38:41]
	v_mfma_f32_16x16x32_bf16 v[34:37], v[172:175], v[188:191], v[34:37]
	v_mfma_f32_16x16x32_bf16 v[22:25], v[164:167], v[206:209], v[22:25]
	v_mfma_f32_16x16x32_bf16 v[18:21], v[172:175], v[206:209], v[18:21]
	v_mfma_f32_16x16x32_bf16 v[6:9], v[164:167], v[214:217], v[6:9]
	v_mfma_f32_16x16x32_bf16 v[2:5], v[172:175], v[214:217], v[2:5]
	v_mfma_f32_16x16x32_bf16 v[54:57], v[168:171], v[184:187], v[54:57]
	v_mfma_f32_16x16x32_bf16 v[50:53], v[176:179], v[184:187], v[50:53]
	v_mfma_f32_16x16x32_bf16 v[38:41], v[168:171], v[192:195], v[38:41]
	v_mfma_f32_16x16x32_bf16 v[34:37], v[176:179], v[192:195], v[34:37]
	v_mfma_f32_16x16x32_bf16 v[22:25], v[168:171], v[210:213], v[22:25]
	v_mfma_f32_16x16x32_bf16 v[18:21], v[176:179], v[210:213], v[18:21]
	v_mfma_f32_16x16x32_bf16 v[6:9], v[168:171], v[218:221], v[6:9]
	v_mfma_f32_16x16x32_bf16 v[2:5], v[176:179], v[218:221], v[2:5]
	s_setprio 0
	s_barrier
	s_add_u32 s26, s26, 0x80000
	s_addc_u32 s27, s27, 0
	s_add_u32 s100, s26, 0xfff80000
	s_addc_u32 s101, s27, -1
	s_add_i32 s2, 0, 0x18000
	s_add_i32 s45, 0, 0x1c000
	v_add_u32_e32 v160, s2, v148
	v_add_u32_e32 v176, s45, v148
	ds_read_b128 v[140:143], v160
	ds_read_b128 v[152:155], v160 offset:1024
	ds_read_b128 v[156:159], v160 offset:2048
	ds_read_b128 v[160:163], v160 offset:3072
	ds_read_b128 v[164:167], v176
	ds_read_b128 v[168:171], v176 offset:1024
	ds_read_b128 v[172:175], v176 offset:2048
	ds_read_b128 v[176:179], v176 offset:3072
	s_mov_b32 m0, s31
	ds_read_b128 v[180:183], v151 offset:32768
	ds_read_b128 v[184:187], v151 offset:33792
	ds_read_b128 v[188:191], v151 offset:34816
	ds_read_b128 v[192:195], v151 offset:35840
	ds_read_b128 v[206:209], v151 offset:36864
	ds_read_b128 v[210:213], v151 offset:37888
	ds_read_b128 v[214:217], v151 offset:38912
	ds_read_b128 v[218:221], v151 offset:39936
	s_mov_b32 m0, s29
	s_nop 0
	global_load_lds_dwordx4 v134, s[100:101]
	s_mov_b32 m0, s30
	s_nop 0
	global_load_lds_dwordx4 v132, s[100:101]
	s_mov_b32 m0, s31
	s_nop 0
	global_load_lds_dwordx4 v134, s[26:27]
	s_mov_b32 m0, s33
	s_nop 0
	global_load_lds_dwordx4 v132, s[26:27]
	s_waitcnt vmcnt(8)
	s_waitcnt lgkmcnt(0)
	s_barrier
	s_setprio 1
	s_waitcnt lgkmcnt(0)
	v_mfma_f32_16x16x32_bf16 v[126:129], v[140:143], v[180:183], v[126:129]
	v_mfma_f32_16x16x32_bf16 v[122:125], v[156:159], v[180:183], v[122:125]
	v_mfma_f32_16x16x32_bf16 v[110:113], v[140:143], v[188:191], v[110:113]
	v_mfma_f32_16x16x32_bf16 v[106:109], v[156:159], v[188:191], v[106:109]
	v_mfma_f32_16x16x32_bf16 v[94:97], v[140:143], v[206:209], v[94:97]
	v_mfma_f32_16x16x32_bf16 v[90:93], v[156:159], v[206:209], v[90:93]
	v_mfma_f32_16x16x32_bf16 v[78:81], v[140:143], v[214:217], v[78:81]
	v_mfma_f32_16x16x32_bf16 v[74:77], v[156:159], v[214:217], v[74:77]
	v_mfma_f32_16x16x32_bf16 v[126:129], v[152:155], v[184:187], v[126:129]
	v_mfma_f32_16x16x32_bf16 v[122:125], v[160:163], v[184:187], v[122:125]
	v_mfma_f32_16x16x32_bf16 v[110:113], v[152:155], v[192:195], v[110:113]
	v_mfma_f32_16x16x32_bf16 v[106:109], v[160:163], v[192:195], v[106:109]
	v_mfma_f32_16x16x32_bf16 v[94:97], v[152:155], v[210:213], v[94:97]
	v_mfma_f32_16x16x32_bf16 v[90:93], v[160:163], v[210:213], v[90:93]
	v_mfma_f32_16x16x32_bf16 v[78:81], v[152:155], v[218:221], v[78:81]
	v_mfma_f32_16x16x32_bf16 v[74:77], v[160:163], v[218:221], v[74:77]
	s_setprio 0
	s_setprio 1
	v_mfma_f32_16x16x32_bf16 v[118:121], v[164:167], v[180:183], v[118:121]
	v_mfma_f32_16x16x32_bf16 v[114:117], v[172:175], v[180:183], v[114:117]
	v_mfma_f32_16x16x32_bf16 v[102:105], v[164:167], v[188:191], v[102:105]
	v_mfma_f32_16x16x32_bf16 v[98:101], v[172:175], v[188:191], v[98:101]
	v_mfma_f32_16x16x32_bf16 v[86:89], v[164:167], v[206:209], v[86:89]
	v_mfma_f32_16x16x32_bf16 v[82:85], v[172:175], v[206:209], v[82:85]
	v_mfma_f32_16x16x32_bf16 v[70:73], v[164:167], v[214:217], v[70:73]
	v_mfma_f32_16x16x32_bf16 v[66:69], v[172:175], v[214:217], v[66:69]
	v_mfma_f32_16x16x32_bf16 v[118:121], v[168:171], v[184:187], v[118:121]
	v_mfma_f32_16x16x32_bf16 v[114:117], v[176:179], v[184:187], v[114:117]
	v_mfma_f32_16x16x32_bf16 v[102:105], v[168:171], v[192:195], v[102:105]
	v_mfma_f32_16x16x32_bf16 v[98:101], v[176:179], v[192:195], v[98:101]
	v_mfma_f32_16x16x32_bf16 v[86:89], v[168:171], v[210:213], v[86:89]
	v_mfma_f32_16x16x32_bf16 v[82:85], v[176:179], v[210:213], v[82:85]
	v_mfma_f32_16x16x32_bf16 v[70:73], v[168:171], v[218:221], v[70:73]
	v_mfma_f32_16x16x32_bf16 v[66:69], v[176:179], v[218:221], v[66:69]
	s_setprio 0
	s_barrier
	s_add_u32 s22, s22, 0x80080
	s_addc_u32 s23, s23, 0
	s_add_u32 s46, s46, 0xfff80080
	s_addc_u32 s47, s47, -1
	s_add_i32 s2, s2, s28
	s_mov_b32 m0, s2
	ds_read_b128 v[180:183], v151 offset:49152
	ds_read_b128 v[184:187], v151 offset:50176
	ds_read_b128 v[188:191], v151 offset:51200
	ds_read_b128 v[192:195], v151 offset:52224
	ds_read_b128 v[206:209], v151 offset:53248
	ds_read_b128 v[210:213], v151 offset:54272
	ds_read_b128 v[214:217], v151 offset:55296
	ds_read_b128 v[218:221], v151 offset:56320
	global_load_lds_dwordx4 v0, s[46:47]
	s_add_i32 m0, s2, 0x2000
	s_add_i32 s2, s45, s28
	global_load_lds_dwordx4 v130, s[46:47]
	s_mov_b32 m0, s2
	s_nop 0
	global_load_lds_dwordx4 v0, s[22:23]
	s_add_i32 m0, s2, 0x2000
	s_nop 0
	global_load_lds_dwordx4 v130, s[22:23]
	s_waitcnt vmcnt(6)
	s_waitcnt lgkmcnt(0)
	s_barrier
	s_setprio 1
	s_waitcnt lgkmcnt(0)
	v_mfma_f32_16x16x32_bf16 v[62:65], v[140:143], v[180:183], v[62:65]
	v_mfma_f32_16x16x32_bf16 v[58:61], v[156:159], v[180:183], v[58:61]
	v_mfma_f32_16x16x32_bf16 v[46:49], v[140:143], v[188:191], v[46:49]
	v_mfma_f32_16x16x32_bf16 v[42:45], v[156:159], v[188:191], v[42:45]
	v_mfma_f32_16x16x32_bf16 v[30:33], v[140:143], v[206:209], v[30:33]
	v_mfma_f32_16x16x32_bf16 v[26:29], v[156:159], v[206:209], v[26:29]
	v_mfma_f32_16x16x32_bf16 v[14:17], v[140:143], v[214:217], v[14:17]
	v_mfma_f32_16x16x32_bf16 v[10:13], v[156:159], v[214:217], v[10:13]
	v_mfma_f32_16x16x32_bf16 v[62:65], v[152:155], v[184:187], v[62:65]
	v_mfma_f32_16x16x32_bf16 v[58:61], v[160:163], v[184:187], v[58:61]
	v_mfma_f32_16x16x32_bf16 v[46:49], v[152:155], v[192:195], v[46:49]
	v_mfma_f32_16x16x32_bf16 v[42:45], v[160:163], v[192:195], v[42:45]
	v_mfma_f32_16x16x32_bf16 v[30:33], v[152:155], v[210:213], v[30:33]
	v_mfma_f32_16x16x32_bf16 v[26:29], v[160:163], v[210:213], v[26:29]
	v_mfma_f32_16x16x32_bf16 v[14:17], v[152:155], v[218:221], v[14:17]
	v_mfma_f32_16x16x32_bf16 v[10:13], v[160:163], v[218:221], v[10:13]
	s_setprio 0
	s_setprio 1
	v_mfma_f32_16x16x32_bf16 v[54:57], v[164:167], v[180:183], v[54:57]
	v_mfma_f32_16x16x32_bf16 v[50:53], v[172:175], v[180:183], v[50:53]
	v_mfma_f32_16x16x32_bf16 v[38:41], v[164:167], v[188:191], v[38:41]
	v_mfma_f32_16x16x32_bf16 v[34:37], v[172:175], v[188:191], v[34:37]
	v_mfma_f32_16x16x32_bf16 v[22:25], v[164:167], v[206:209], v[22:25]
	v_mfma_f32_16x16x32_bf16 v[18:21], v[172:175], v[206:209], v[18:21]
	v_mfma_f32_16x16x32_bf16 v[6:9], v[164:167], v[214:217], v[6:9]
	v_mfma_f32_16x16x32_bf16 v[2:5], v[172:175], v[214:217], v[2:5]
	v_mfma_f32_16x16x32_bf16 v[54:57], v[168:171], v[184:187], v[54:57]
	v_mfma_f32_16x16x32_bf16 v[50:53], v[176:179], v[184:187], v[50:53]
	v_mfma_f32_16x16x32_bf16 v[38:41], v[168:171], v[192:195], v[38:41]
	v_mfma_f32_16x16x32_bf16 v[34:37], v[176:179], v[192:195], v[34:37]
	v_mfma_f32_16x16x32_bf16 v[22:25], v[168:171], v[210:213], v[22:25]
	v_mfma_f32_16x16x32_bf16 v[18:21], v[176:179], v[210:213], v[18:21]
	v_mfma_f32_16x16x32_bf16 v[6:9], v[168:171], v[218:221], v[6:9]
	v_mfma_f32_16x16x32_bf16 v[2:5], v[176:179], v[218:221], v[2:5]
	s_setprio 0
	s_barrier
	s_add_i32 s44, s44, 2
	s_add_u32 s24, s24, 0x100
	s_addc_u32 s25, s25, 0
	s_add_u32 s42, s42, 0x100
	s_addc_u32 s43, s43, 0
	s_cmp_gt_u32 s44, 29
	s_cbranch_scc0 .LBB0_408
	s_nop 0
	s_and_b64 vcc, exec, s[12:13]
	s_cbranch_vccz .LBB0_411
	s_barrier

.LBB0_440:
	s_add_u32 s2, s18, 0xfff80080
	s_addc_u32 s10, s19, -1
	s_add_i32 s47, 0, 0x10000
	s_cmp_eq_u32 s46, 28
	s_cselect_b32 s29, s25, s10
	s_cselect_b32 s28, s34, s2
	s_cselect_b32 s11, s23, s45
	s_cselect_b32 s10, s43, s44
	s_add_u32 s100, s18, 0xfff80000
	s_addc_u32 s101, s19, -1
	s_add_i32 s2, 0, 0x14000
	v_add_u32_e32 v154, s47, v162
	v_add_u32_e32 v184, s2, v162
	ds_read_b128 v[130:133], v154
	ds_read_b128 v[134:137], v154 offset:1024
	ds_read_b128 v[150:153], v154 offset:2048
	ds_read_b128 v[154:157], v154 offset:3072
	ds_read_b128 v[158:161], v184
	ds_read_b128 v[176:179], v184 offset:1024
	ds_read_b128 v[180:183], v184 offset:2048
	ds_read_b128 v[184:187], v184 offset:3072
	s_add_i32 m0, s31, 0xc000
	ds_read_b128 v[188:191], v175
	ds_read_b128 v[192:195], v175 offset:1024
	ds_read_b128 v[206:209], v175 offset:2048
	ds_read_b128 v[210:213], v175 offset:3072
	ds_read_b128 v[214:217], v175 offset:4096
	ds_read_b128 v[218:221], v175 offset:5120
	ds_read_b128 v[222:225], v175 offset:6144
	ds_read_b128 v[226:229], v175 offset:7168
	s_mov_b32 m0, s38
	s_nop 0
	global_load_lds_dwordx4 v144, s[100:101]
	s_mov_b32 m0, s39
	s_nop 0
	global_load_lds_dwordx4 v148, s[100:101]
	s_add_i32 m0, s31, 0xc000
	s_nop 0
	global_load_lds_dwordx4 v144, s[18:19]
	s_add_i32 m0, s31, 0xe000
	s_nop 0
	global_load_lds_dwordx4 v148, s[18:19]
	s_waitcnt vmcnt(8)
	s_waitcnt lgkmcnt(0)
	s_barrier
	s_setprio 1
	s_waitcnt lgkmcnt(0)
	v_mfma_f32_16x16x32_bf16 v[126:129], v[130:133], v[188:191], v[126:129]
	v_mfma_f32_16x16x32_bf16 v[122:125], v[150:153], v[188:191], v[122:125]
	v_mfma_f32_16x16x32_bf16 v[110:113], v[130:133], v[206:209], v[110:113]
	v_mfma_f32_16x16x32_bf16 v[106:109], v[150:153], v[206:209], v[106:109]
	v_mfma_f32_16x16x32_bf16 v[94:97], v[130:133], v[214:217], v[94:97]
	v_mfma_f32_16x16x32_bf16 v[90:93], v[150:153], v[214:217], v[90:93]
	v_mfma_f32_16x16x32_bf16 v[78:81], v[130:133], v[222:225], v[78:81]
	v_mfma_f32_16x16x32_bf16 v[74:77], v[150:153], v[222:225], v[74:77]
	v_mfma_f32_16x16x32_bf16 v[126:129], v[134:137], v[192:195], v[126:129]
	v_mfma_f32_16x16x32_bf16 v[122:125], v[154:157], v[192:195], v[122:125]
	v_mfma_f32_16x16x32_bf16 v[110:113], v[134:137], v[210:213], v[110:113]
	v_mfma_f32_16x16x32_bf16 v[106:109], v[154:157], v[210:213], v[106:109]
	v_mfma_f32_16x16x32_bf16 v[94:97], v[134:137], v[218:221], v[94:97]
	v_mfma_f32_16x16x32_bf16 v[90:93], v[154:157], v[218:221], v[90:93]
	v_mfma_f32_16x16x32_bf16 v[78:81], v[134:137], v[226:229], v[78:81]
	v_mfma_f32_16x16x32_bf16 v[74:77], v[154:157], v[226:229], v[74:77]
	s_setprio 0
	s_setprio 1
	v_mfma_f32_16x16x32_bf16 v[118:121], v[158:161], v[188:191], v[118:121]
	v_mfma_f32_16x16x32_bf16 v[114:117], v[180:183], v[188:191], v[114:117]
	v_mfma_f32_16x16x32_bf16 v[102:105], v[158:161], v[206:209], v[102:105]
	v_mfma_f32_16x16x32_bf16 v[98:101], v[180:183], v[206:209], v[98:101]
	v_mfma_f32_16x16x32_bf16 v[86:89], v[158:161], v[214:217], v[86:89]
	v_mfma_f32_16x16x32_bf16 v[82:85], v[180:183], v[214:217], v[82:85]
	v_mfma_f32_16x16x32_bf16 v[70:73], v[158:161], v[222:225], v[70:73]
	v_mfma_f32_16x16x32_bf16 v[66:69], v[180:183], v[222:225], v[66:69]
	v_mfma_f32_16x16x32_bf16 v[118:121], v[176:179], v[192:195], v[118:121]
	v_mfma_f32_16x16x32_bf16 v[114:117], v[184:187], v[192:195], v[114:117]
	v_mfma_f32_16x16x32_bf16 v[102:105], v[176:179], v[210:213], v[102:105]
	v_mfma_f32_16x16x32_bf16 v[98:101], v[184:187], v[210:213], v[98:101]
	v_mfma_f32_16x16x32_bf16 v[86:89], v[176:179], v[218:221], v[86:89]
	v_mfma_f32_16x16x32_bf16 v[82:85], v[184:187], v[218:221], v[82:85]
	v_mfma_f32_16x16x32_bf16 v[70:73], v[176:179], v[226:229], v[70:73]
	v_mfma_f32_16x16x32_bf16 v[66:69], v[184:187], v[226:229], v[66:69]
	s_setprio 0
	s_barrier
	s_add_u32 s52, s10, 0x80000
	s_addc_u32 s53, s11, 0
	s_add_i32 s47, s47, s30
	s_mov_b32 m0, s47
	ds_read_b128 v[188:191], v175 offset:16384
	ds_read_b128 v[192:195], v175 offset:17408
	ds_read_b128 v[206:209], v175 offset:18432
	ds_read_b128 v[210:213], v175 offset:19456
	ds_read_b128 v[214:217], v175 offset:20480
	ds_read_b128 v[218:221], v175 offset:21504
	ds_read_b128 v[222:225], v175 offset:22528
	ds_read_b128 v[226:229], v175 offset:23552
	global_load_lds_dwordx4 v0, s[10:11]
	s_add_i32 m0, s47, 0x2000
	s_add_i32 s2, s2, s30
	global_load_lds_dwordx4 v138, s[10:11]
	s_mov_b32 m0, s2
	s_nop 0
	global_load_lds_dwordx4 v0, s[52:53]
	s_add_i32 m0, s2, 0x2000
	s_nop 0
	global_load_lds_dwordx4 v138, s[52:53]
	s_waitcnt vmcnt(6)
	s_waitcnt lgkmcnt(0)
	s_barrier
	s_setprio 1
	s_waitcnt lgkmcnt(0)
	v_mfma_f32_16x16x32_bf16 v[62:65], v[130:133], v[188:191], v[62:65]
	v_mfma_f32_16x16x32_bf16 v[58:61], v[150:153], v[188:191], v[58:61]
	v_mfma_f32_16x16x32_bf16 v[46:49], v[130:133], v[206:209], v[46:49]
	v_mfma_f32_16x16x32_bf16 v[42:45], v[150:153], v[206:209], v[42:45]
	v_mfma_f32_16x16x32_bf16 v[30:33], v[130:133], v[214:217], v[30:33]
	v_mfma_f32_16x16x32_bf16 v[26:29], v[150:153], v[214:217], v[26:29]
	v_mfma_f32_16x16x32_bf16 v[14:17], v[130:133], v[222:225], v[14:17]
	v_mfma_f32_16x16x32_bf16 v[10:13], v[150:153], v[222:225], v[10:13]
	v_mfma_f32_16x16x32_bf16 v[62:65], v[134:137], v[192:195], v[62:65]
	v_mfma_f32_16x16x32_bf16 v[58:61], v[154:157], v[192:195], v[58:61]
	v_mfma_f32_16x16x32_bf16 v[46:49], v[134:137], v[210:213], v[46:49]
	v_mfma_f32_16x16x32_bf16 v[42:45], v[154:157], v[210:213], v[42:45]
	v_mfma_f32_16x16x32_bf16 v[30:33], v[134:137], v[218:221], v[30:33]
	v_mfma_f32_16x16x32_bf16 v[26:29], v[154:157], v[218:221], v[26:29]
	v_mfma_f32_16x16x32_bf16 v[14:17], v[134:137], v[226:229], v[14:17]
	v_mfma_f32_16x16x32_bf16 v[10:13], v[154:157], v[226:229], v[10:13]
	s_setprio 0
	s_setprio 1
	v_mfma_f32_16x16x32_bf16 v[54:57], v[158:161], v[188:191], v[54:57]
	v_mfma_f32_16x16x32_bf16 v[50:53], v[180:183], v[188:191], v[50:53]
	v_mfma_f32_16x16x32_bf16 v[38:41], v[158:161], v[206:209], v[38:41]
	v_mfma_f32_16x16x32_bf16 v[34:37], v[180:183], v[206:209], v[34:37]
	v_mfma_f32_16x16x32_bf16 v[22:25], v[158:161], v[214:217], v[22:25]
	v_mfma_f32_16x16x32_bf16 v[18:21], v[180:183], v[214:217], v[18:21]
	v_mfma_f32_16x16x32_bf16 v[6:9], v[158:161], v[222:225], v[6:9]
	v_mfma_f32_16x16x32_bf16 v[2:5], v[180:183], v[222:225], v[2:5]
	v_mfma_f32_16x16x32_bf16 v[54:57], v[176:179], v[192:195], v[54:57]
	v_mfma_f32_16x16x32_bf16 v[50:53], v[184:187], v[192:195], v[50:53]
	v_mfma_f32_16x16x32_bf16 v[38:41], v[176:179], v[210:213], v[38:41]
	v_mfma_f32_16x16x32_bf16 v[34:37], v[184:187], v[210:213], v[34:37]
	v_mfma_f32_16x16x32_bf16 v[22:25], v[176:179], v[218:221], v[22:25]
	v_mfma_f32_16x16x32_bf16 v[18:21], v[184:187], v[218:221], v[18:21]
	v_mfma_f32_16x16x32_bf16 v[6:9], v[176:179], v[226:229], v[6:9]
	v_mfma_f32_16x16x32_bf16 v[2:5], v[184:187], v[226:229], v[2:5]
	s_setprio 0
	s_barrier
	s_add_u32 s28, s28, 0x80000
	s_addc_u32 s29, s29, 0
	s_add_u32 s100, s28, 0xfff80000
	s_addc_u32 s101, s29, -1
	s_add_i32 s2, 0, 0x18000
	s_add_i32 s47, 0, 0x1c000
	v_add_u32_e32 v154, s2, v162
	v_add_u32_e32 v184, s47, v162
	ds_read_b128 v[130:133], v154
	ds_read_b128 v[134:137], v154 offset:1024
	ds_read_b128 v[150:153], v154 offset:2048
	ds_read_b128 v[154:157], v154 offset:3072
	ds_read_b128 v[158:161], v184
	ds_read_b128 v[176:179], v184 offset:1024
	ds_read_b128 v[180:183], v184 offset:2048
	ds_read_b128 v[184:187], v184 offset:3072
	s_mov_b32 m0, s36
	ds_read_b128 v[188:191], v175 offset:32768
	ds_read_b128 v[192:195], v175 offset:33792
	ds_read_b128 v[206:209], v175 offset:34816
	ds_read_b128 v[210:213], v175 offset:35840
	ds_read_b128 v[214:217], v175 offset:36864
	ds_read_b128 v[218:221], v175 offset:37888
	ds_read_b128 v[222:225], v175 offset:38912
	ds_read_b128 v[226:229], v175 offset:39936
	s_mov_b32 m0, s31
	s_nop 0
	global_load_lds_dwordx4 v142, s[100:101]
	s_mov_b32 m0, s35
	s_nop 0
	global_load_lds_dwordx4 v140, s[100:101]
	s_mov_b32 m0, s36
	s_nop 0
	global_load_lds_dwordx4 v142, s[28:29]
	s_mov_b32 m0, s37
	s_nop 0
	global_load_lds_dwordx4 v140, s[28:29]
	s_waitcnt vmcnt(8)
	s_waitcnt lgkmcnt(0)
	s_barrier
	s_setprio 1
	s_waitcnt lgkmcnt(0)
	v_mfma_f32_16x16x32_bf16 v[126:129], v[130:133], v[188:191], v[126:129]
	v_mfma_f32_16x16x32_bf16 v[122:125], v[150:153], v[188:191], v[122:125]
	v_mfma_f32_16x16x32_bf16 v[110:113], v[130:133], v[206:209], v[110:113]
	v_mfma_f32_16x16x32_bf16 v[106:109], v[150:153], v[206:209], v[106:109]
	v_mfma_f32_16x16x32_bf16 v[94:97], v[130:133], v[214:217], v[94:97]
	v_mfma_f32_16x16x32_bf16 v[90:93], v[150:153], v[214:217], v[90:93]
	v_mfma_f32_16x16x32_bf16 v[78:81], v[130:133], v[222:225], v[78:81]
	v_mfma_f32_16x16x32_bf16 v[74:77], v[150:153], v[222:225], v[74:77]
	v_mfma_f32_16x16x32_bf16 v[126:129], v[134:137], v[192:195], v[126:129]
	v_mfma_f32_16x16x32_bf16 v[122:125], v[154:157], v[192:195], v[122:125]
	v_mfma_f32_16x16x32_bf16 v[110:113], v[134:137], v[210:213], v[110:113]
	v_mfma_f32_16x16x32_bf16 v[106:109], v[154:157], v[210:213], v[106:109]
	v_mfma_f32_16x16x32_bf16 v[94:97], v[134:137], v[218:221], v[94:97]
	v_mfma_f32_16x16x32_bf16 v[90:93], v[154:157], v[218:221], v[90:93]
	v_mfma_f32_16x16x32_bf16 v[78:81], v[134:137], v[226:229], v[78:81]
	v_mfma_f32_16x16x32_bf16 v[74:77], v[154:157], v[226:229], v[74:77]
	s_setprio 0
	s_setprio 1
	v_mfma_f32_16x16x32_bf16 v[118:121], v[158:161], v[188:191], v[118:121]
	v_mfma_f32_16x16x32_bf16 v[114:117], v[180:183], v[188:191], v[114:117]
	v_mfma_f32_16x16x32_bf16 v[102:105], v[158:161], v[206:209], v[102:105]
	v_mfma_f32_16x16x32_bf16 v[98:101], v[180:183], v[206:209], v[98:101]
	v_mfma_f32_16x16x32_bf16 v[86:89], v[158:161], v[214:217], v[86:89]
	v_mfma_f32_16x16x32_bf16 v[82:85], v[180:183], v[214:217], v[82:85]
	v_mfma_f32_16x16x32_bf16 v[70:73], v[158:161], v[222:225], v[70:73]
	v_mfma_f32_16x16x32_bf16 v[66:69], v[180:183], v[222:225], v[66:69]
	v_mfma_f32_16x16x32_bf16 v[118:121], v[176:179], v[192:195], v[118:121]
	v_mfma_f32_16x16x32_bf16 v[114:117], v[184:187], v[192:195], v[114:117]
	v_mfma_f32_16x16x32_bf16 v[102:105], v[176:179], v[210:213], v[102:105]
	v_mfma_f32_16x16x32_bf16 v[98:101], v[184:187], v[210:213], v[98:101]
	v_mfma_f32_16x16x32_bf16 v[86:89], v[176:179], v[218:221], v[86:89]
	v_mfma_f32_16x16x32_bf16 v[82:85], v[184:187], v[218:221], v[82:85]
	v_mfma_f32_16x16x32_bf16 v[70:73], v[176:179], v[226:229], v[70:73]
	v_mfma_f32_16x16x32_bf16 v[66:69], v[184:187], v[226:229], v[66:69]
	s_setprio 0
	s_barrier
	s_add_u32 s10, s10, 0x80080
	s_addc_u32 s11, s11, 0
	s_add_u32 s52, s52, 0xfff80080
	s_addc_u32 s53, s53, -1
	s_add_i32 s2, s2, s30
	s_mov_b32 m0, s2
	ds_read_b128 v[188:191], v175 offset:49152
	ds_read_b128 v[192:195], v175 offset:50176
	ds_read_b128 v[206:209], v175 offset:51200
	ds_read_b128 v[210:213], v175 offset:52224
	ds_read_b128 v[214:217], v175 offset:53248
	ds_read_b128 v[218:221], v175 offset:54272
	ds_read_b128 v[222:225], v175 offset:55296
	ds_read_b128 v[226:229], v175 offset:56320
	global_load_lds_dwordx4 v0, s[52:53]
	s_add_i32 m0, s2, 0x2000
	s_add_i32 s2, s47, s30
	global_load_lds_dwordx4 v138, s[52:53]
	s_mov_b32 m0, s2
	s_nop 0
	global_load_lds_dwordx4 v0, s[10:11]
	s_add_i32 m0, s2, 0x2000
	s_nop 0
	global_load_lds_dwordx4 v138, s[10:11]
	s_waitcnt vmcnt(6)
	s_waitcnt lgkmcnt(0)
	s_barrier
	s_setprio 1
	s_waitcnt lgkmcnt(0)
	v_mfma_f32_16x16x32_bf16 v[62:65], v[130:133], v[188:191], v[62:65]
	v_mfma_f32_16x16x32_bf16 v[58:61], v[150:153], v[188:191], v[58:61]
	v_mfma_f32_16x16x32_bf16 v[46:49], v[130:133], v[206:209], v[46:49]
	v_mfma_f32_16x16x32_bf16 v[42:45], v[150:153], v[206:209], v[42:45]
	v_mfma_f32_16x16x32_bf16 v[30:33], v[130:133], v[214:217], v[30:33]
	v_mfma_f32_16x16x32_bf16 v[26:29], v[150:153], v[214:217], v[26:29]
	v_mfma_f32_16x16x32_bf16 v[14:17], v[130:133], v[222:225], v[14:17]
	v_mfma_f32_16x16x32_bf16 v[10:13], v[150:153], v[222:225], v[10:13]
	v_mfma_f32_16x16x32_bf16 v[62:65], v[134:137], v[192:195], v[62:65]
	v_mfma_f32_16x16x32_bf16 v[58:61], v[154:157], v[192:195], v[58:61]
	v_mfma_f32_16x16x32_bf16 v[46:49], v[134:137], v[210:213], v[46:49]
	v_mfma_f32_16x16x32_bf16 v[42:45], v[154:157], v[210:213], v[42:45]
	v_mfma_f32_16x16x32_bf16 v[30:33], v[134:137], v[218:221], v[30:33]
	v_mfma_f32_16x16x32_bf16 v[26:29], v[154:157], v[218:221], v[26:29]
	v_mfma_f32_16x16x32_bf16 v[14:17], v[134:137], v[226:229], v[14:17]
	v_mfma_f32_16x16x32_bf16 v[10:13], v[154:157], v[226:229], v[10:13]
	s_setprio 0
	s_setprio 1
	v_mfma_f32_16x16x32_bf16 v[54:57], v[158:161], v[188:191], v[54:57]
	v_mfma_f32_16x16x32_bf16 v[50:53], v[180:183], v[188:191], v[50:53]
	v_mfma_f32_16x16x32_bf16 v[38:41], v[158:161], v[206:209], v[38:41]
	v_mfma_f32_16x16x32_bf16 v[34:37], v[180:183], v[206:209], v[34:37]
	v_mfma_f32_16x16x32_bf16 v[22:25], v[158:161], v[214:217], v[22:25]
	v_mfma_f32_16x16x32_bf16 v[18:21], v[180:183], v[214:217], v[18:21]
	v_mfma_f32_16x16x32_bf16 v[6:9], v[158:161], v[222:225], v[6:9]
	v_mfma_f32_16x16x32_bf16 v[2:5], v[180:183], v[222:225], v[2:5]
	v_mfma_f32_16x16x32_bf16 v[54:57], v[176:179], v[192:195], v[54:57]
	v_mfma_f32_16x16x32_bf16 v[50:53], v[184:187], v[192:195], v[50:53]
	v_mfma_f32_16x16x32_bf16 v[38:41], v[176:179], v[210:213], v[38:41]
	v_mfma_f32_16x16x32_bf16 v[34:37], v[184:187], v[210:213], v[34:37]
	v_mfma_f32_16x16x32_bf16 v[22:25], v[176:179], v[218:221], v[22:25]
	v_mfma_f32_16x16x32_bf16 v[18:21], v[184:187], v[218:221], v[18:21]
	v_mfma_f32_16x16x32_bf16 v[6:9], v[176:179], v[226:229], v[6:9]
	v_mfma_f32_16x16x32_bf16 v[2:5], v[184:187], v[226:229], v[2:5]
	s_setprio 0
	s_barrier
	s_add_i32 s46, s46, 2
	s_add_u32 s18, s18, 0x100
	s_addc_u32 s19, s19, 0
	s_add_u32 s44, s44, 0x100
	s_addc_u32 s45, s45, 0
	s_cmp_gt_u32 s46, 29
	s_cbranch_scc0 .LBB0_440
	s_nop 0
	s_and_b64 vcc, exec, s[20:21]
	s_cbranch_vccz .LBB0_443
	s_barrier

.LBB0_1102:
	s_add_u32 s2, s22, 0xfff80080
	s_addc_u32 s20, s23, -1
	s_add_i32 s45, 0, 0x10000
	s_cmp_eq_u32 s44, 28
	s_cselect_b32 s25, s15, s20
	s_cselect_b32 s24, s40, s2
	s_cselect_b32 s21, s13, s43
	s_cselect_b32 s20, s41, s42
	s_add_u32 s100, s22, 0xfff80000
	s_addc_u32 s101, s23, -1
	s_add_i32 s2, 0, 0x14000
	v_add_u32_e32 v142, s45, v226
	v_add_u32_e32 v160, s2, v226
	ds_read_b128 v[130:133], v142
	ds_read_b128 v[134:137], v142 offset:1024
	ds_read_b128 v[138:141], v142 offset:2048
	ds_read_b128 v[142:145], v142 offset:3072
	ds_read_b128 v[148:151], v160
	ds_read_b128 v[152:155], v160 offset:1024
	ds_read_b128 v[156:159], v160 offset:2048
	ds_read_b128 v[160:163], v160 offset:3072
	s_add_i32 m0, s30, 0xc000
	ds_read_b128 v[164:167], v228
	ds_read_b128 v[168:171], v228 offset:1024
	ds_read_b128 v[172:175], v228 offset:2048
	ds_read_b128 v[176:179], v228 offset:3072
	ds_read_b128 v[180:183], v228 offset:4096
	ds_read_b128 v[184:187], v228 offset:5120
	ds_read_b128 v[208:211], v228 offset:6144
	ds_read_b128 v[212:215], v228 offset:7168
	s_mov_b32 m0, s38
	s_nop 0
	global_load_lds_dwordx4 v194, s[100:101]
	s_mov_b32 m0, s39
	s_nop 0
	global_load_lds_dwordx4 v206, s[100:101]
	s_add_i32 m0, s30, 0xc000
	s_nop 0
	global_load_lds_dwordx4 v194, s[22:23]
	s_add_i32 m0, s30, 0xe000
	s_nop 0
	global_load_lds_dwordx4 v206, s[22:23]
	s_waitcnt vmcnt(8)
	s_waitcnt lgkmcnt(0)
	s_barrier
	s_setprio 1
	s_waitcnt lgkmcnt(0)
	v_mfma_f32_16x16x32_bf16 v[126:129], v[130:133], v[164:167], v[126:129]
	v_mfma_f32_16x16x32_bf16 v[122:125], v[138:141], v[164:167], v[122:125]
	v_mfma_f32_16x16x32_bf16 v[110:113], v[130:133], v[172:175], v[110:113]
	v_mfma_f32_16x16x32_bf16 v[106:109], v[138:141], v[172:175], v[106:109]
	v_mfma_f32_16x16x32_bf16 v[94:97], v[130:133], v[180:183], v[94:97]
	v_mfma_f32_16x16x32_bf16 v[90:93], v[138:141], v[180:183], v[90:93]
	v_mfma_f32_16x16x32_bf16 v[78:81], v[130:133], v[208:211], v[78:81]
	v_mfma_f32_16x16x32_bf16 v[74:77], v[138:141], v[208:211], v[74:77]
	v_mfma_f32_16x16x32_bf16 v[126:129], v[134:137], v[168:171], v[126:129]
	v_mfma_f32_16x16x32_bf16 v[122:125], v[142:145], v[168:171], v[122:125]
	v_mfma_f32_16x16x32_bf16 v[110:113], v[134:137], v[176:179], v[110:113]
	v_mfma_f32_16x16x32_bf16 v[106:109], v[142:145], v[176:179], v[106:109]
	v_mfma_f32_16x16x32_bf16 v[94:97], v[134:137], v[184:187], v[94:97]
	v_mfma_f32_16x16x32_bf16 v[90:93], v[142:145], v[184:187], v[90:93]
	v_mfma_f32_16x16x32_bf16 v[78:81], v[134:137], v[212:215], v[78:81]
	v_mfma_f32_16x16x32_bf16 v[74:77], v[142:145], v[212:215], v[74:77]
	s_setprio 0
	s_setprio 1
	v_mfma_f32_16x16x32_bf16 v[118:121], v[148:151], v[164:167], v[118:121]
	v_mfma_f32_16x16x32_bf16 v[114:117], v[156:159], v[164:167], v[114:117]
	v_mfma_f32_16x16x32_bf16 v[102:105], v[148:151], v[172:175], v[102:105]
	v_mfma_f32_16x16x32_bf16 v[98:101], v[156:159], v[172:175], v[98:101]
	v_mfma_f32_16x16x32_bf16 v[86:89], v[148:151], v[180:183], v[86:89]
	v_mfma_f32_16x16x32_bf16 v[82:85], v[156:159], v[180:183], v[82:85]
	v_mfma_f32_16x16x32_bf16 v[70:73], v[148:151], v[208:211], v[70:73]
	v_mfma_f32_16x16x32_bf16 v[66:69], v[156:159], v[208:211], v[66:69]
	v_mfma_f32_16x16x32_bf16 v[118:121], v[152:155], v[168:171], v[118:121]
	v_mfma_f32_16x16x32_bf16 v[114:117], v[160:163], v[168:171], v[114:117]
	v_mfma_f32_16x16x32_bf16 v[102:105], v[152:155], v[176:179], v[102:105]
	v_mfma_f32_16x16x32_bf16 v[98:101], v[160:163], v[176:179], v[98:101]
	v_mfma_f32_16x16x32_bf16 v[86:89], v[152:155], v[184:187], v[86:89]
	v_mfma_f32_16x16x32_bf16 v[82:85], v[160:163], v[184:187], v[82:85]
	v_mfma_f32_16x16x32_bf16 v[70:73], v[152:155], v[212:215], v[70:73]
	v_mfma_f32_16x16x32_bf16 v[66:69], v[160:163], v[212:215], v[66:69]
	s_setprio 0
	s_barrier
	s_add_u32 s46, s20, 0x80000
	s_addc_u32 s47, s21, 0
	s_add_i32 s45, s45, s29
	s_mov_b32 m0, s45
	ds_read_b128 v[164:167], v228 offset:16384
	ds_read_b128 v[168:171], v228 offset:17408
	ds_read_b128 v[172:175], v228 offset:18432
	ds_read_b128 v[176:179], v228 offset:19456
	ds_read_b128 v[180:183], v228 offset:20480
	ds_read_b128 v[184:187], v228 offset:21504
	ds_read_b128 v[208:211], v228 offset:22528
	ds_read_b128 v[212:215], v228 offset:23552
	global_load_lds_dwordx4 v0, s[20:21]
	s_add_i32 m0, s45, 0x2000
	s_add_i32 s2, s2, s29
	global_load_lds_dwordx4 v188, s[20:21]
	s_mov_b32 m0, s2
	s_nop 0
	global_load_lds_dwordx4 v0, s[46:47]
	s_add_i32 m0, s2, 0x2000
	s_nop 0
	global_load_lds_dwordx4 v188, s[46:47]
	s_waitcnt vmcnt(6)
	s_waitcnt lgkmcnt(0)
	s_barrier
	s_setprio 1
	s_waitcnt lgkmcnt(0)
	v_mfma_f32_16x16x32_bf16 v[62:65], v[130:133], v[164:167], v[62:65]
	v_mfma_f32_16x16x32_bf16 v[58:61], v[138:141], v[164:167], v[58:61]
	v_mfma_f32_16x16x32_bf16 v[46:49], v[130:133], v[172:175], v[46:49]
	v_mfma_f32_16x16x32_bf16 v[42:45], v[138:141], v[172:175], v[42:45]
	v_mfma_f32_16x16x32_bf16 v[30:33], v[130:133], v[180:183], v[30:33]
	v_mfma_f32_16x16x32_bf16 v[26:29], v[138:141], v[180:183], v[26:29]
	v_mfma_f32_16x16x32_bf16 v[14:17], v[130:133], v[208:211], v[14:17]
	v_mfma_f32_16x16x32_bf16 v[10:13], v[138:141], v[208:211], v[10:13]
	v_mfma_f32_16x16x32_bf16 v[62:65], v[134:137], v[168:171], v[62:65]
	v_mfma_f32_16x16x32_bf16 v[58:61], v[142:145], v[168:171], v[58:61]
	v_mfma_f32_16x16x32_bf16 v[46:49], v[134:137], v[176:179], v[46:49]
	v_mfma_f32_16x16x32_bf16 v[42:45], v[142:145], v[176:179], v[42:45]
	v_mfma_f32_16x16x32_bf16 v[30:33], v[134:137], v[184:187], v[30:33]
	v_mfma_f32_16x16x32_bf16 v[26:29], v[142:145], v[184:187], v[26:29]
	v_mfma_f32_16x16x32_bf16 v[14:17], v[134:137], v[212:215], v[14:17]
	v_mfma_f32_16x16x32_bf16 v[10:13], v[142:145], v[212:215], v[10:13]
	s_setprio 0
	s_setprio 1
	v_mfma_f32_16x16x32_bf16 v[54:57], v[148:151], v[164:167], v[54:57]
	v_mfma_f32_16x16x32_bf16 v[50:53], v[156:159], v[164:167], v[50:53]
	v_mfma_f32_16x16x32_bf16 v[38:41], v[148:151], v[172:175], v[38:41]
	v_mfma_f32_16x16x32_bf16 v[34:37], v[156:159], v[172:175], v[34:37]
	v_mfma_f32_16x16x32_bf16 v[22:25], v[148:151], v[180:183], v[22:25]
	v_mfma_f32_16x16x32_bf16 v[18:21], v[156:159], v[180:183], v[18:21]
	v_mfma_f32_16x16x32_bf16 v[6:9], v[148:151], v[208:211], v[6:9]
	v_mfma_f32_16x16x32_bf16 v[2:5], v[156:159], v[208:211], v[2:5]
	v_mfma_f32_16x16x32_bf16 v[54:57], v[152:155], v[168:171], v[54:57]
	v_mfma_f32_16x16x32_bf16 v[50:53], v[160:163], v[168:171], v[50:53]
	v_mfma_f32_16x16x32_bf16 v[38:41], v[152:155], v[176:179], v[38:41]
	v_mfma_f32_16x16x32_bf16 v[34:37], v[160:163], v[176:179], v[34:37]
	v_mfma_f32_16x16x32_bf16 v[22:25], v[152:155], v[184:187], v[22:25]
	v_mfma_f32_16x16x32_bf16 v[18:21], v[160:163], v[184:187], v[18:21]
	v_mfma_f32_16x16x32_bf16 v[6:9], v[152:155], v[212:215], v[6:9]
	v_mfma_f32_16x16x32_bf16 v[2:5], v[160:163], v[212:215], v[2:5]
	s_setprio 0
	s_barrier
	s_add_u32 s24, s24, 0x80000
	s_addc_u32 s25, s25, 0
	s_add_u32 s100, s24, 0xfff80000
	s_addc_u32 s101, s25, -1
	s_add_i32 s2, 0, 0x18000
	s_add_i32 s45, 0, 0x1c000
	v_add_u32_e32 v142, s2, v226
	v_add_u32_e32 v160, s45, v226
	ds_read_b128 v[130:133], v142
	ds_read_b128 v[134:137], v142 offset:1024
	ds_read_b128 v[138:141], v142 offset:2048
	ds_read_b128 v[142:145], v142 offset:3072
	ds_read_b128 v[148:151], v160
	ds_read_b128 v[152:155], v160 offset:1024
	ds_read_b128 v[156:159], v160 offset:2048
	ds_read_b128 v[160:163], v160 offset:3072
	s_mov_b32 m0, s35
	ds_read_b128 v[164:167], v228 offset:32768
	ds_read_b128 v[168:171], v228 offset:33792
	ds_read_b128 v[172:175], v228 offset:34816
	ds_read_b128 v[176:179], v228 offset:35840
	ds_read_b128 v[180:183], v228 offset:36864
	ds_read_b128 v[184:187], v228 offset:37888
	ds_read_b128 v[208:211], v228 offset:38912
	ds_read_b128 v[212:215], v228 offset:39936
	s_mov_b32 m0, s30
	s_nop 0
	global_load_lds_dwordx4 v192, s[100:101]
	s_mov_b32 m0, s31
	s_nop 0
	global_load_lds_dwordx4 v190, s[100:101]
	s_mov_b32 m0, s35
	s_nop 0
	global_load_lds_dwordx4 v192, s[24:25]
	s_mov_b32 m0, s36
	s_nop 0
	global_load_lds_dwordx4 v190, s[24:25]
	s_waitcnt vmcnt(8)
	s_waitcnt lgkmcnt(0)
	s_barrier
	s_setprio 1
	s_waitcnt lgkmcnt(0)
	v_mfma_f32_16x16x32_bf16 v[126:129], v[130:133], v[164:167], v[126:129]
	v_mfma_f32_16x16x32_bf16 v[122:125], v[138:141], v[164:167], v[122:125]
	v_mfma_f32_16x16x32_bf16 v[110:113], v[130:133], v[172:175], v[110:113]
	v_mfma_f32_16x16x32_bf16 v[106:109], v[138:141], v[172:175], v[106:109]
	v_mfma_f32_16x16x32_bf16 v[94:97], v[130:133], v[180:183], v[94:97]
	v_mfma_f32_16x16x32_bf16 v[90:93], v[138:141], v[180:183], v[90:93]
	v_mfma_f32_16x16x32_bf16 v[78:81], v[130:133], v[208:211], v[78:81]
	v_mfma_f32_16x16x32_bf16 v[74:77], v[138:141], v[208:211], v[74:77]
	v_mfma_f32_16x16x32_bf16 v[126:129], v[134:137], v[168:171], v[126:129]
	v_mfma_f32_16x16x32_bf16 v[122:125], v[142:145], v[168:171], v[122:125]
	v_mfma_f32_16x16x32_bf16 v[110:113], v[134:137], v[176:179], v[110:113]
	v_mfma_f32_16x16x32_bf16 v[106:109], v[142:145], v[176:179], v[106:109]
	v_mfma_f32_16x16x32_bf16 v[94:97], v[134:137], v[184:187], v[94:97]
	v_mfma_f32_16x16x32_bf16 v[90:93], v[142:145], v[184:187], v[90:93]
	v_mfma_f32_16x16x32_bf16 v[78:81], v[134:137], v[212:215], v[78:81]
	v_mfma_f32_16x16x32_bf16 v[74:77], v[142:145], v[212:215], v[74:77]
	s_setprio 0
	s_setprio 1
	v_mfma_f32_16x16x32_bf16 v[118:121], v[148:151], v[164:167], v[118:121]
	v_mfma_f32_16x16x32_bf16 v[114:117], v[156:159], v[164:167], v[114:117]
	v_mfma_f32_16x16x32_bf16 v[102:105], v[148:151], v[172:175], v[102:105]
	v_mfma_f32_16x16x32_bf16 v[98:101], v[156:159], v[172:175], v[98:101]
	v_mfma_f32_16x16x32_bf16 v[86:89], v[148:151], v[180:183], v[86:89]
	v_mfma_f32_16x16x32_bf16 v[82:85], v[156:159], v[180:183], v[82:85]
	v_mfma_f32_16x16x32_bf16 v[70:73], v[148:151], v[208:211], v[70:73]
	v_mfma_f32_16x16x32_bf16 v[66:69], v[156:159], v[208:211], v[66:69]
	v_mfma_f32_16x16x32_bf16 v[118:121], v[152:155], v[168:171], v[118:121]
	v_mfma_f32_16x16x32_bf16 v[114:117], v[160:163], v[168:171], v[114:117]
	v_mfma_f32_16x16x32_bf16 v[102:105], v[152:155], v[176:179], v[102:105]
	v_mfma_f32_16x16x32_bf16 v[98:101], v[160:163], v[176:179], v[98:101]
	v_mfma_f32_16x16x32_bf16 v[86:89], v[152:155], v[184:187], v[86:89]
	v_mfma_f32_16x16x32_bf16 v[82:85], v[160:163], v[184:187], v[82:85]
	v_mfma_f32_16x16x32_bf16 v[70:73], v[152:155], v[212:215], v[70:73]
	v_mfma_f32_16x16x32_bf16 v[66:69], v[160:163], v[212:215], v[66:69]
	s_setprio 0
	s_barrier
	s_add_u32 s20, s20, 0x80080
	s_addc_u32 s21, s21, 0
	s_add_u32 s46, s46, 0xfff80080
	s_addc_u32 s47, s47, -1
	s_add_i32 s2, s2, s29
	s_mov_b32 m0, s2
	ds_read_b128 v[164:167], v228 offset:49152
	ds_read_b128 v[168:171], v228 offset:50176
	ds_read_b128 v[172:175], v228 offset:51200
	ds_read_b128 v[176:179], v228 offset:52224
	ds_read_b128 v[180:183], v228 offset:53248
	ds_read_b128 v[184:187], v228 offset:54272
	ds_read_b128 v[208:211], v228 offset:55296
	ds_read_b128 v[212:215], v228 offset:56320
	global_load_lds_dwordx4 v0, s[46:47]
	s_add_i32 m0, s2, 0x2000
	s_add_i32 s2, s45, s29
	global_load_lds_dwordx4 v188, s[46:47]
	s_mov_b32 m0, s2
	s_nop 0
	global_load_lds_dwordx4 v0, s[20:21]
	s_add_i32 m0, s2, 0x2000
	s_nop 0
	global_load_lds_dwordx4 v188, s[20:21]
	s_waitcnt vmcnt(6)
	s_waitcnt lgkmcnt(0)
	s_barrier
	s_setprio 1
	s_waitcnt lgkmcnt(0)
	v_mfma_f32_16x16x32_bf16 v[62:65], v[130:133], v[164:167], v[62:65]
	v_mfma_f32_16x16x32_bf16 v[58:61], v[138:141], v[164:167], v[58:61]
	v_mfma_f32_16x16x32_bf16 v[46:49], v[130:133], v[172:175], v[46:49]
	v_mfma_f32_16x16x32_bf16 v[42:45], v[138:141], v[172:175], v[42:45]
	v_mfma_f32_16x16x32_bf16 v[30:33], v[130:133], v[180:183], v[30:33]
	v_mfma_f32_16x16x32_bf16 v[26:29], v[138:141], v[180:183], v[26:29]
	v_mfma_f32_16x16x32_bf16 v[14:17], v[130:133], v[208:211], v[14:17]
	v_mfma_f32_16x16x32_bf16 v[10:13], v[138:141], v[208:211], v[10:13]
	v_mfma_f32_16x16x32_bf16 v[62:65], v[134:137], v[168:171], v[62:65]
	v_mfma_f32_16x16x32_bf16 v[58:61], v[142:145], v[168:171], v[58:61]
	v_mfma_f32_16x16x32_bf16 v[46:49], v[134:137], v[176:179], v[46:49]
	v_mfma_f32_16x16x32_bf16 v[42:45], v[142:145], v[176:179], v[42:45]
	v_mfma_f32_16x16x32_bf16 v[30:33], v[134:137], v[184:187], v[30:33]
	v_mfma_f32_16x16x32_bf16 v[26:29], v[142:145], v[184:187], v[26:29]
	v_mfma_f32_16x16x32_bf16 v[14:17], v[134:137], v[212:215], v[14:17]
	v_mfma_f32_16x16x32_bf16 v[10:13], v[142:145], v[212:215], v[10:13]
	s_setprio 0
	s_setprio 1
	v_mfma_f32_16x16x32_bf16 v[54:57], v[148:151], v[164:167], v[54:57]
	v_mfma_f32_16x16x32_bf16 v[50:53], v[156:159], v[164:167], v[50:53]
	v_mfma_f32_16x16x32_bf16 v[38:41], v[148:151], v[172:175], v[38:41]
	v_mfma_f32_16x16x32_bf16 v[34:37], v[156:159], v[172:175], v[34:37]
	v_mfma_f32_16x16x32_bf16 v[22:25], v[148:151], v[180:183], v[22:25]
	v_mfma_f32_16x16x32_bf16 v[18:21], v[156:159], v[180:183], v[18:21]
	v_mfma_f32_16x16x32_bf16 v[6:9], v[148:151], v[208:211], v[6:9]
	v_mfma_f32_16x16x32_bf16 v[2:5], v[156:159], v[208:211], v[2:5]
	v_mfma_f32_16x16x32_bf16 v[54:57], v[152:155], v[168:171], v[54:57]
	v_mfma_f32_16x16x32_bf16 v[50:53], v[160:163], v[168:171], v[50:53]
	v_mfma_f32_16x16x32_bf16 v[38:41], v[152:155], v[176:179], v[38:41]
	v_mfma_f32_16x16x32_bf16 v[34:37], v[160:163], v[176:179], v[34:37]
	v_mfma_f32_16x16x32_bf16 v[22:25], v[152:155], v[184:187], v[22:25]
	v_mfma_f32_16x16x32_bf16 v[18:21], v[160:163], v[184:187], v[18:21]
	v_mfma_f32_16x16x32_bf16 v[6:9], v[152:155], v[212:215], v[6:9]
	v_mfma_f32_16x16x32_bf16 v[2:5], v[160:163], v[212:215], v[2:5]
	s_setprio 0
	s_barrier
	s_add_i32 s44, s44, 2
	s_add_u32 s22, s22, 0x100
	s_addc_u32 s23, s23, 0
	s_add_u32 s42, s42, 0x100
	s_addc_u32 s43, s43, 0
	s_cmp_gt_u32 s44, 29
	s_cbranch_scc0 .LBB0_1102
	s_nop 0
	v_lshl_or_b32 v210, s3, 8, v227
	v_lshl_add_u32 v224, s34, 8, v147
	v_ashrrev_i32_e32 v211, 31, v210
	v_lshlrev_b64 v[130:131], 1, v[210:211]
	v_ashrrev_i32_e32 v225, 31, v224
	v_lshl_add_u64 v[132:133], s[8:9], 0, v[130:131]
	v_lshlrev_b64 v[134:135], 12, v[224:225]
	v_lshl_add_u64 v[136:137], v[132:133], 0, v[134:135]
	global_load_dwordx4 v[240:243], v[136:137], off
	global_load_dwordx4 v[244:247], v[136:137], off offset:256
	v_or_b32_e32 v222, 16, v224
	v_or_b32_e32 v220, 32, v224
	v_or_b32_e32 v218, 48, v224
	v_add_u32_e32 v216, 0x80, v224
	v_add_u32_e32 v214, 0x90, v224
	v_add_u32_e32 v212, 0xa0, v224
	v_add_u32_e32 v208, 0xb0, v224
	v_ashrrev_i32_e32 v223, 31, v222
	v_ashrrev_i32_e32 v221, 31, v220
	v_ashrrev_i32_e32 v219, 31, v218
	v_ashrrev_i32_e32 v217, 31, v216
	v_ashrrev_i32_e32 v215, 31, v214
	v_ashrrev_i32_e32 v213, 31, v212
	v_ashrrev_i32_e32 v209, 31, v208
	v_lshlrev_b64 v[136:137], 12, v[222:223]
	v_lshlrev_b64 v[138:139], 12, v[220:221]
	v_lshlrev_b64 v[140:141], 12, v[218:219]
	v_lshlrev_b64 v[142:143], 12, v[216:217]
	v_lshlrev_b64 v[144:145], 12, v[214:215]
	v_lshlrev_b64 v[148:149], 12, v[212:213]
	v_lshlrev_b64 v[150:151], 12, v[208:209]
	v_lshl_add_u64 v[134:135], s[8:9], 0, v[134:135]
	v_lshl_add_u64 v[136:137], v[132:133], 0, v[136:137]
	v_lshl_add_u64 v[138:139], v[132:133], 0, v[138:139]
	v_lshl_add_u64 v[140:141], v[132:133], 0, v[140:141]
	v_lshl_add_u64 v[142:143], v[132:133], 0, v[142:143]
	v_lshl_add_u64 v[144:145], v[132:133], 0, v[144:145]
	v_lshl_add_u64 v[236:237], v[132:133], 0, v[148:149]
	v_lshl_add_u64 v[132:133], v[132:133], 0, v[150:151]
	v_lshl_add_u64 v[248:249], v[134:135], 0, v[130:131]
	global_load_dwordx4 v[184:187], v[136:137], off
	global_load_dwordx4 v[180:183], v[136:137], off offset:256
	global_load_dwordx4 v[176:179], v[138:139], off
	global_load_dwordx4 v[172:175], v[138:139], off offset:256
	global_load_dwordx4 v[168:171], v[140:141], off
	global_load_dwordx4 v[164:167], v[140:141], off offset:256
	global_load_dwordx4 v[160:163], v[142:143], off
	global_load_dwordx4 v[156:159], v[142:143], off offset:256
	global_load_dwordx4 v[152:155], v[144:145], off
	global_load_dwordx4 v[148:151], v[144:145], off offset:256
	s_nop 0
	global_load_dwordx4 v[142:145], v[236:237], off
	global_load_dwordx4 v[138:141], v[236:237], off offset:256
	global_load_dwordx4 v[134:137], v[132:133], off
	s_nop 0
	global_load_dwordx4 v[130:133], v[132:133], off offset:256
	s_lshl_b32 s20, s3, 2
	s_ashr_i32 s21, s20, 31
	s_waitcnt vmcnt(0)
	v_lshlrev_b32_e32 v236, 16, v240
	v_and_b32_e32 v237, 0xffff0000, v240
	v_lshlrev_b32_e32 v250, 16, v242
	v_and_b32_e32 v251, 0xffff0000, v242
	v_lshlrev_b32_e32 v242, 16, v243
	v_and_b32_e32 v243, 0xffff0000, v243
	v_lshlrev_b32_e32 v240, 16, v241
	v_and_b32_e32 v241, 0xffff0000, v241
	v_pk_add_f32 v[126:127], v[126:127], v[236:237]
	v_pk_add_f32 v[236:237], v[124:125], v[242:243]
	v_pk_add_f32 v[124:125], v[122:123], v[250:251]
	v_pk_add_f32 v[128:129], v[128:129], v[240:241]
	v_cvt_pk_bf16_f32 v122, v126, v127
	v_lshlrev_b32_e32 v252, 16, v244
	v_cvt_pk_bf16_f32 v123, v128, v129
	v_cvt_pk_bf16_f32 v124, v124, v125
	v_cvt_pk_bf16_f32 v125, v236, v237
	global_store_dwordx4 v[248:249], v[122:125], off
	v_lshlrev_b32_e32 v126, 16, v122
	v_lshlrev_b32_e32 v127, 16, v123
	v_and_b32_e32 v122, 0xffff0000, v122
	v_and_b32_e32 v123, 0xffff0000, v123
	v_lshlrev_b32_e32 v128, 16, v124
	v_and_b32_e32 v124, 0xffff0000, v124
	v_lshlrev_b32_e32 v129, 16, v125
	v_and_b32_e32 v125, 0xffff0000, v125
	v_mul_f32_e32 v122, v122, v122
	v_mul_f32_e32 v123, v123, v123
	v_mul_f32_e32 v124, v124, v124
	v_mul_f32_e32 v125, v125, v125
	v_fmac_f32_e32 v122, v126, v126
	v_fmac_f32_e32 v123, v127, v127
	v_fmac_f32_e32 v124, v128, v128
	v_fmac_f32_e32 v125, v129, v129
	v_add_f32_e32 v122, v122, v123
	v_add_f32_e32 v123, v124, v125
	v_and_b32_e32 v253, 0xffff0000, v244
	v_add_f32_e32 v128, v122, v123
	v_lshlrev_b32_e32 v122, 16, v245
	v_and_b32_e32 v123, 0xffff0000, v245
	v_lshlrev_b32_e32 v124, 16, v246
	v_and_b32_e32 v125, 0xffff0000, v246
	v_lshlrev_b32_e32 v126, 16, v247
	v_and_b32_e32 v127, 0xffff0000, v247
	v_pk_add_f32 v[120:121], v[120:121], v[122:123]
	v_pk_add_f32 v[118:119], v[118:119], v[252:253]
	v_pk_add_f32 v[122:123], v[116:117], v[126:127]
	v_pk_add_f32 v[116:117], v[114:115], v[124:125]
	v_cvt_pk_bf16_f32 v114, v118, v119
	v_cvt_pk_bf16_f32 v115, v120, v121
	s_nop 0
	v_cvt_pk_bf16_f32 v116, v116, v117
	v_cvt_pk_bf16_f32 v117, v122, v123
	global_store_dwordx4 v[248:249], v[114:117], off offset:256
	v_lshlrev_b32_e32 v118, 16, v114
	v_lshlrev_b32_e32 v119, 16, v115
	v_and_b32_e32 v114, 0xffff0000, v114
	v_and_b32_e32 v115, 0xffff0000, v115
	v_mul_f32_e32 v114, v114, v114
	v_mul_f32_e32 v115, v115, v115
	v_lshlrev_b32_e32 v120, 16, v116
	v_and_b32_e32 v116, 0xffff0000, v116
	v_lshlrev_b32_e32 v121, 16, v117
	v_and_b32_e32 v117, 0xffff0000, v117
	v_fmac_f32_e32 v114, v118, v118
	v_fmac_f32_e32 v115, v119, v119
	v_add_f32_e32 v114, v114, v115
	v_mul_f32_e32 v115, v116, v116
	v_mul_f32_e32 v116, v117, v117
	v_fmac_f32_e32 v115, v120, v120
	v_fmac_f32_e32 v116, v121, v121
	v_add_f32_e32 v115, v115, v116
	v_add_f32_e32 v114, v114, v115
	s_mov_b32 s2, 0
	v_add_f32_e32 v114, v128, v114
	v_mbcnt_lo_u32_b32 v115, -1, s2
	v_mbcnt_hi_u32_b32 v115, -1, v115
	v_lshlrev_b32_e32 v115, 2, v115
	v_xor_b32_e32 v115, 64, v115
	ds_bpermute_b32 v115, v115, v114
	s_mov_b32 s2, 0
	s_waitcnt lgkmcnt(0)
	v_add_f32_e32 v114, v114, v115
	v_mbcnt_lo_u32_b32 v115, -1, s2
	v_mbcnt_hi_u32_b32 v115, -1, v115
	v_lshlrev_b32_e32 v115, 2, v115
	v_xor_b32_e32 v115, 0x80, v115
	ds_bpermute_b32 v115, v115, v114
	s_and_saveexec_b64 s[22:23], s[4:5]
	s_cbranch_execz .LBB0_1105
	v_lshlrev_b64 v[116:117], 7, v[224:225]
	v_lshl_add_u64 v[116:117], s[10:11], 0, v[116:117]
	v_lshl_add_u64 v[116:117], s[20:21], 2, v[116:117]
	s_lshl_b32 s50, s37, 2
	v_lshl_add_u64 v[116:117], v[116:117], 0, s[50:51]
	s_waitcnt lgkmcnt(0)
	v_add_f32_e32 v114, v114, v115
	global_store_dword v[116:117], v114, off

	.amdhsa_kernel _Z6mk_fwd4Args
		.amdhsa_group_segment_fixed_size 0
		.amdhsa_private_segment_fixed_size 0
		.amdhsa_kernarg_size 424
		.amdhsa_user_sgpr_count 2
		.amdhsa_user_sgpr_dispatch_ptr 0
		.amdhsa_user_sgpr_queue_ptr 0
		.amdhsa_user_sgpr_kernarg_segment_ptr 1
		.amdhsa_user_sgpr_dispatch_id 0
		.amdhsa_user_sgpr_kernarg_preload_length 0
		.amdhsa_user_sgpr_kernarg_preload_offset 0
		.amdhsa_user_sgpr_private_segment_size 0
		.amdhsa_uses_dynamic_stack 0
		.amdhsa_enable_private_segment 0
		.amdhsa_system_sgpr_workgroup_id_x 1
		.amdhsa_system_sgpr_workgroup_id_y 0
		.amdhsa_system_sgpr_workgroup_id_z 0
		.amdhsa_system_sgpr_workgroup_info 0
		.amdhsa_system_vgpr_workitem_id 0
		.amdhsa_next_free_vgpr 256
		.amdhsa_next_free_sgpr 102
		.amdhsa_accum_offset 256
		.amdhsa_reserve_vcc 1
		.amdhsa_float_round_mode_32 0
		.amdhsa_float_round_mode_16_64 0
		.amdhsa_float_denorm_mode_32 3
		.amdhsa_float_denorm_mode_16_64 3
		.amdhsa_dx10_clamp 1
		.amdhsa_ieee_mode 1
		.amdhsa_fp16_overflow 0
		.amdhsa_tg_split 0
		.amdhsa_exception_fp_ieee_invalid_op 0
		.amdhsa_exception_fp_denorm_src 0
		.amdhsa_exception_fp_ieee_div_zero 0
		.amdhsa_exception_fp_ieee_overflow 0
		.amdhsa_exception_fp_ieee_underflow 0
		.amdhsa_exception_fp_ieee_inexact 0
		.amdhsa_exception_int_div_zero 0
	.end_amdhsa_kernel

amdhsa.kernels:
  - .agpr_count:     0
    .args:
      - .offset:         0
        .size:           168
        .value_kind:     by_value
      - .offset:         168
        .size:           4
        .value_kind:     hidden_block_count_x
      - .offset:         172
        .size:           4
        .value_kind:     hidden_block_count_y
      - .offset:         176
        .size:           4
        .value_kind:     hidden_block_count_z
      - .offset:         180
        .size:           2
        .value_kind:     hidden_group_size_x
      - .offset:         182
        .size:           2
        .value_kind:     hidden_group_size_y
      - .offset:         184
        .size:           2
        .value_kind:     hidden_group_size_z
      - .offset:         186
        .size:           2
        .value_kind:     hidden_remainder_x
      - .offset:         188
        .size:           2
        .value_kind:     hidden_remainder_y
      - .offset:         190
        .size:           2
        .value_kind:     hidden_remainder_z
      - .offset:         208
        .size:           8
        .value_kind:     hidden_global_offset_x
      - .offset:         216
        .size:           8
        .value_kind:     hidden_global_offset_y
      - .offset:         224
        .size:           8
        .value_kind:     hidden_global_offset_z
      - .offset:         232
        .size:           2
        .value_kind:     hidden_grid_dims
      - .offset:         288
        .size:           4
        .value_kind:     hidden_dynamic_lds_size
    .group_segment_fixed_size: 0
    .kernarg_segment_align: 8
    .kernarg_segment_size: 424
    .language:       OpenCL C
    .language_version:
      - 2
      - 0
    .max_flat_workgroup_size: 512
    .name:           _Z6mk_fwd4Args
    .private_segment_fixed_size: 0
    .sgpr_count:     108
    .sgpr_spill_count: 109
    .symbol:         _Z6mk_fwd4Args.kd
    .uniform_work_group_size: 1
    .uses_dynamic_stack: false
    .vgpr_count:     256
    .vgpr_spill_count: 0
    .wavefront_size: 64
